# plus: last K-loop iteration of a workgroup's last tile issues no next-tile prefetch DMAs (third loop-body copy, waits re-derived)
# baseline (speedup 1.0000x reference)
.Lc0s_final:
	s_add_i32 s62, s58, 0xfff80080
	s_and_b64 s[10:11], s[10:11], exec
	s_cselect_b32 s78, s54, s62
	s_cselect_b32 s62, s55, s60
	s_add_i32 s10, 0, 0x10000
	v_add_u32_e32 v0, s10, v157
	v_add_u32_e32 v147, s10, v158
	s_add_i32 s10, 0, 0x14000
	ds_read_b128 v[164:167], v0
	ds_read_b128 v[168:171], v0 offset:2048
	ds_read_b128 v[172:175], v147
	ds_read_b128 v[176:179], v147 offset:2048
	v_add_u32_e32 v0, s10, v157
	v_add_u32_e32 v147, s10, v158
	ds_read_b128 v[180:183], v0
	ds_read_b128 v[184:187], v0 offset:2048
	ds_read_b128 v[188:191], v147
	ds_read_b128 v[192:195], v147 offset:2048
	s_or_b32 s64, s78, 0x80
	s_or_b32 s65, s62, 0x80
	s_mov_b32 m0, s41
	ds_read_b128 v[196:199], v161
	ds_read_b128 v[204:207], v161 offset:2048
	ds_read_b128 v[208:211], v162
	ds_read_b128 v[212:215], v162 offset:2048
	ds_read_b128 v[216:219], v161 offset:4096
	ds_read_b128 v[220:223], v161 offset:6144
	ds_read_b128 v[224:227], v162 offset:4096
	ds_read_b128 v[228:231], v162 offset:6144
	buffer_load_dwordx4 v153, s[48:51], s58 offen lds
	s_mov_b32 m0, s42
	s_nop 0
	buffer_load_dwordx4 v155, s[48:51], s58 offen lds
	s_waitcnt vmcnt(8)
	s_waitcnt lgkmcnt(0)
	s_barrier
	s_setprio 1
	s_waitcnt lgkmcnt(0)
	v_mfma_f32_16x16x32_f16 v[118:121], v[164:167], v[196:199], v[118:121]
	v_mfma_f32_16x16x32_f16 v[110:113], v[168:171], v[196:199], v[110:113]
	v_mfma_f32_16x16x32_f16 v[102:105], v[164:167], v[204:207], v[102:105]
	v_mfma_f32_16x16x32_f16 v[94:97], v[168:171], v[204:207], v[94:97]
	v_mfma_f32_16x16x32_f16 v[86:89], v[164:167], v[216:219], v[86:89]
	v_mfma_f32_16x16x32_f16 v[78:81], v[168:171], v[216:219], v[78:81]
	v_mfma_f32_16x16x32_f16 v[66:69], v[164:167], v[220:223], v[66:69]
	v_mfma_f32_16x16x32_f16 v[58:61], v[168:171], v[220:223], v[58:61]
	v_mfma_f32_16x16x32_f16 v[118:121], v[172:175], v[208:211], v[118:121]
	v_mfma_f32_16x16x32_f16 v[110:113], v[176:179], v[208:211], v[110:113]
	v_mfma_f32_16x16x32_f16 v[102:105], v[172:175], v[212:215], v[102:105]
	v_mfma_f32_16x16x32_f16 v[94:97], v[176:179], v[212:215], v[94:97]
	v_mfma_f32_16x16x32_f16 v[86:89], v[172:175], v[224:227], v[86:89]
	v_mfma_f32_16x16x32_f16 v[78:81], v[176:179], v[224:227], v[78:81]
	v_mfma_f32_16x16x32_f16 v[66:69], v[172:175], v[228:231], v[66:69]
	v_mfma_f32_16x16x32_f16 v[58:61], v[176:179], v[228:231], v[58:61]
	s_setprio 0
	s_setprio 1
	v_mfma_f32_16x16x32_f16 v[126:129], v[180:183], v[196:199], v[126:129]
	v_mfma_f32_16x16x32_f16 v[122:125], v[184:187], v[196:199], v[122:125]
	v_mfma_f32_16x16x32_f16 v[114:117], v[180:183], v[204:207], v[114:117]
	v_mfma_f32_16x16x32_f16 v[106:109], v[184:187], v[204:207], v[106:109]
	v_mfma_f32_16x16x32_f16 v[98:101], v[180:183], v[216:219], v[98:101]
	v_mfma_f32_16x16x32_f16 v[90:93], v[184:187], v[216:219], v[90:93]
	v_mfma_f32_16x16x32_f16 v[82:85], v[180:183], v[220:223], v[82:85]
	v_mfma_f32_16x16x32_f16 v[74:77], v[184:187], v[220:223], v[74:77]
	v_mfma_f32_16x16x32_f16 v[126:129], v[188:191], v[208:211], v[126:129]
	v_mfma_f32_16x16x32_f16 v[122:125], v[192:195], v[208:211], v[122:125]
	v_mfma_f32_16x16x32_f16 v[114:117], v[188:191], v[212:215], v[114:117]
	v_mfma_f32_16x16x32_f16 v[106:109], v[192:195], v[212:215], v[106:109]
	v_mfma_f32_16x16x32_f16 v[98:101], v[188:191], v[224:227], v[98:101]
	v_mfma_f32_16x16x32_f16 v[90:93], v[192:195], v[224:227], v[90:93]
	v_mfma_f32_16x16x32_f16 v[82:85], v[188:191], v[228:231], v[82:85]
	v_mfma_f32_16x16x32_f16 v[74:77], v[192:195], v[228:231], v[74:77]
	s_setprio 0
	s_barrier
	s_mov_b32 s10, s50
	s_mov_b32 s11, s51
	ds_read_b128 v[196:199], v161 offset:16384
	ds_read_b128 v[204:207], v161 offset:18432
	ds_read_b128 v[208:211], v162 offset:16384
	ds_read_b128 v[212:215], v162 offset:18432
	ds_read_b128 v[216:219], v161 offset:20480
	ds_read_b128 v[220:223], v161 offset:22528
	ds_read_b128 v[224:227], v162 offset:20480
	ds_read_b128 v[228:231], v162 offset:22528
	s_add_i32 s81, s62, 0x80000
	s_waitcnt vmcnt(2)
	s_waitcnt lgkmcnt(0)
	s_barrier
	s_setprio 1
	s_waitcnt lgkmcnt(0)
	v_mfma_f32_16x16x32_f16 v[54:57], v[164:167], v[196:199], v[54:57]
	v_mfma_f32_16x16x32_f16 v[46:49], v[168:171], v[196:199], v[46:49]
	v_mfma_f32_16x16x32_f16 v[38:41], v[164:167], v[204:207], v[38:41]
	v_mfma_f32_16x16x32_f16 v[30:33], v[168:171], v[204:207], v[30:33]
	v_mfma_f32_16x16x32_f16 v[22:25], v[164:167], v[216:219], v[22:25]
	v_mfma_f32_16x16x32_f16 v[14:17], v[168:171], v[216:219], v[14:17]
	v_mfma_f32_16x16x32_f16 v[6:9], v[164:167], v[220:223], v[6:9]
	v_mfma_f32_16x16x32_f16 v[2:5], v[168:171], v[220:223], v[2:5]
	v_mfma_f32_16x16x32_f16 v[54:57], v[172:175], v[208:211], v[54:57]
	v_mfma_f32_16x16x32_f16 v[46:49], v[176:179], v[208:211], v[46:49]
	v_mfma_f32_16x16x32_f16 v[38:41], v[172:175], v[212:215], v[38:41]
	v_mfma_f32_16x16x32_f16 v[30:33], v[176:179], v[212:215], v[30:33]
	v_mfma_f32_16x16x32_f16 v[22:25], v[172:175], v[224:227], v[22:25]
	v_mfma_f32_16x16x32_f16 v[14:17], v[176:179], v[224:227], v[14:17]
	v_mfma_f32_16x16x32_f16 v[6:9], v[172:175], v[228:231], v[6:9]
	v_mfma_f32_16x16x32_f16 v[2:5], v[176:179], v[228:231], v[2:5]
	s_setprio 0
	s_setprio 1
	v_mfma_f32_16x16x32_f16 v[70:73], v[180:183], v[196:199], v[70:73]
	v_mfma_f32_16x16x32_f16 v[62:65], v[184:187], v[196:199], v[62:65]
	v_mfma_f32_16x16x32_f16 v[50:53], v[180:183], v[204:207], v[50:53]
	v_mfma_f32_16x16x32_f16 v[42:45], v[184:187], v[204:207], v[42:45]
	v_mfma_f32_16x16x32_f16 v[34:37], v[180:183], v[216:219], v[34:37]
	v_mfma_f32_16x16x32_f16 v[26:29], v[184:187], v[216:219], v[26:29]
	v_mfma_f32_16x16x32_f16 v[18:21], v[180:183], v[220:223], v[18:21]
	v_mfma_f32_16x16x32_f16 v[10:13], v[184:187], v[220:223], v[10:13]
	v_mfma_f32_16x16x32_f16 v[70:73], v[188:191], v[208:211], v[70:73]
	v_mfma_f32_16x16x32_f16 v[62:65], v[192:195], v[208:211], v[62:65]
	v_mfma_f32_16x16x32_f16 v[50:53], v[188:191], v[212:215], v[50:53]
	v_mfma_f32_16x16x32_f16 v[42:45], v[192:195], v[212:215], v[42:45]
	v_mfma_f32_16x16x32_f16 v[34:37], v[188:191], v[224:227], v[34:37]
	v_mfma_f32_16x16x32_f16 v[26:29], v[192:195], v[224:227], v[26:29]
	v_mfma_f32_16x16x32_f16 v[18:21], v[188:191], v[228:231], v[18:21]
	v_mfma_f32_16x16x32_f16 v[10:13], v[192:195], v[228:231], v[10:13]
	s_setprio 0
	s_barrier
	s_add_i32 s81, 0, 0x18000
	v_add_u32_e32 v0, s81, v157
	v_add_u32_e32 v147, s81, v158
	s_add_i32 s81, 0, 0x1c000
	ds_read_b128 v[164:167], v0
	ds_read_b128 v[168:171], v0 offset:2048
	ds_read_b128 v[172:175], v147
	ds_read_b128 v[176:179], v147 offset:2048
	v_add_u32_e32 v0, s81, v157
	v_add_u32_e32 v147, s81, v158
	ds_read_b128 v[180:183], v0
	ds_read_b128 v[184:187], v0 offset:2048
	ds_read_b128 v[188:191], v147
	ds_read_b128 v[192:195], v147 offset:2048
	s_add_i32 s78, s78, 0x80000
	ds_read_b128 v[196:199], v161 offset:32768
	ds_read_b128 v[204:207], v161 offset:34816
	ds_read_b128 v[208:211], v162 offset:32768
	ds_read_b128 v[212:215], v162 offset:34816
	ds_read_b128 v[216:219], v161 offset:36864
	ds_read_b128 v[220:223], v161 offset:38912
	ds_read_b128 v[224:227], v162 offset:36864
	ds_read_b128 v[228:231], v162 offset:38912
	s_waitcnt vmcnt(0)
	s_waitcnt lgkmcnt(0)
	s_barrier
	s_setprio 1
	s_waitcnt lgkmcnt(0)
	v_mfma_f32_16x16x32_f16 v[118:121], v[164:167], v[196:199], v[118:121]
	v_mfma_f32_16x16x32_f16 v[110:113], v[168:171], v[196:199], v[110:113]
	v_mfma_f32_16x16x32_f16 v[102:105], v[164:167], v[204:207], v[102:105]
	v_mfma_f32_16x16x32_f16 v[94:97], v[168:171], v[204:207], v[94:97]
	v_mfma_f32_16x16x32_f16 v[86:89], v[164:167], v[216:219], v[86:89]
	v_mfma_f32_16x16x32_f16 v[78:81], v[168:171], v[216:219], v[78:81]
	v_mfma_f32_16x16x32_f16 v[66:69], v[164:167], v[220:223], v[66:69]
	v_mfma_f32_16x16x32_f16 v[58:61], v[168:171], v[220:223], v[58:61]
	v_mfma_f32_16x16x32_f16 v[118:121], v[172:175], v[208:211], v[118:121]
	v_mfma_f32_16x16x32_f16 v[110:113], v[176:179], v[208:211], v[110:113]
	v_mfma_f32_16x16x32_f16 v[102:105], v[172:175], v[212:215], v[102:105]
	v_mfma_f32_16x16x32_f16 v[94:97], v[176:179], v[212:215], v[94:97]
	v_mfma_f32_16x16x32_f16 v[86:89], v[172:175], v[224:227], v[86:89]
	v_mfma_f32_16x16x32_f16 v[78:81], v[176:179], v[224:227], v[78:81]
	v_mfma_f32_16x16x32_f16 v[66:69], v[172:175], v[228:231], v[66:69]
	v_mfma_f32_16x16x32_f16 v[58:61], v[176:179], v[228:231], v[58:61]
	s_setprio 0
	s_setprio 1
	v_mfma_f32_16x16x32_f16 v[126:129], v[180:183], v[196:199], v[126:129]
	v_mfma_f32_16x16x32_f16 v[122:125], v[184:187], v[196:199], v[122:125]
	v_mfma_f32_16x16x32_f16 v[114:117], v[180:183], v[204:207], v[114:117]
	v_mfma_f32_16x16x32_f16 v[106:109], v[184:187], v[204:207], v[106:109]
	v_mfma_f32_16x16x32_f16 v[98:101], v[180:183], v[216:219], v[98:101]
	v_mfma_f32_16x16x32_f16 v[90:93], v[184:187], v[216:219], v[90:93]
	v_mfma_f32_16x16x32_f16 v[82:85], v[180:183], v[220:223], v[82:85]
	v_mfma_f32_16x16x32_f16 v[74:77], v[184:187], v[220:223], v[74:77]
	v_mfma_f32_16x16x32_f16 v[126:129], v[188:191], v[208:211], v[126:129]
	v_mfma_f32_16x16x32_f16 v[122:125], v[192:195], v[208:211], v[122:125]
	v_mfma_f32_16x16x32_f16 v[114:117], v[188:191], v[212:215], v[114:117]
	v_mfma_f32_16x16x32_f16 v[106:109], v[192:195], v[212:215], v[106:109]
	v_mfma_f32_16x16x32_f16 v[98:101], v[188:191], v[224:227], v[98:101]
	v_mfma_f32_16x16x32_f16 v[90:93], v[192:195], v[224:227], v[90:93]
	v_mfma_f32_16x16x32_f16 v[82:85], v[188:191], v[228:231], v[82:85]
	v_mfma_f32_16x16x32_f16 v[74:77], v[192:195], v[228:231], v[74:77]
	s_setprio 0
	s_barrier
	ds_read_b128 v[196:199], v161 offset:49152
	ds_read_b128 v[204:207], v161 offset:51200
	ds_read_b128 v[208:211], v162 offset:49152
	ds_read_b128 v[212:215], v162 offset:51200
	ds_read_b128 v[216:219], v161 offset:53248
	ds_read_b128 v[220:223], v161 offset:55296
	ds_read_b128 v[224:227], v162 offset:53248
	ds_read_b128 v[228:231], v162 offset:55296
	s_add_i32 s62, s62, 0x80080
	s_waitcnt vmcnt(0)
	s_waitcnt lgkmcnt(0)
	s_barrier
	s_setprio 1
	s_waitcnt lgkmcnt(0)
	v_mfma_f32_16x16x32_f16 v[54:57], v[164:167], v[196:199], v[54:57]
	v_mfma_f32_16x16x32_f16 v[46:49], v[168:171], v[196:199], v[46:49]
	v_mfma_f32_16x16x32_f16 v[38:41], v[164:167], v[204:207], v[38:41]
	v_mfma_f32_16x16x32_f16 v[30:33], v[168:171], v[204:207], v[30:33]
	v_mfma_f32_16x16x32_f16 v[22:25], v[164:167], v[216:219], v[22:25]
	v_mfma_f32_16x16x32_f16 v[14:17], v[168:171], v[216:219], v[14:17]
	v_mfma_f32_16x16x32_f16 v[6:9], v[164:167], v[220:223], v[6:9]
	v_mfma_f32_16x16x32_f16 v[2:5], v[168:171], v[220:223], v[2:5]
	v_mfma_f32_16x16x32_f16 v[54:57], v[172:175], v[208:211], v[54:57]
	v_mfma_f32_16x16x32_f16 v[46:49], v[176:179], v[208:211], v[46:49]
	v_mfma_f32_16x16x32_f16 v[38:41], v[172:175], v[212:215], v[38:41]
	v_mfma_f32_16x16x32_f16 v[30:33], v[176:179], v[212:215], v[30:33]
	v_mfma_f32_16x16x32_f16 v[22:25], v[172:175], v[224:227], v[22:25]
	v_mfma_f32_16x16x32_f16 v[14:17], v[176:179], v[224:227], v[14:17]
	v_mfma_f32_16x16x32_f16 v[6:9], v[172:175], v[228:231], v[6:9]
	v_mfma_f32_16x16x32_f16 v[2:5], v[176:179], v[228:231], v[2:5]
	s_setprio 0
	s_setprio 1
	v_mfma_f32_16x16x32_f16 v[70:73], v[180:183], v[196:199], v[70:73]
	v_mfma_f32_16x16x32_f16 v[62:65], v[184:187], v[196:199], v[62:65]
	v_mfma_f32_16x16x32_f16 v[50:53], v[180:183], v[204:207], v[50:53]
	v_mfma_f32_16x16x32_f16 v[42:45], v[184:187], v[204:207], v[42:45]
	v_mfma_f32_16x16x32_f16 v[34:37], v[180:183], v[216:219], v[34:37]
	v_mfma_f32_16x16x32_f16 v[26:29], v[184:187], v[216:219], v[26:29]
	v_mfma_f32_16x16x32_f16 v[18:21], v[180:183], v[220:223], v[18:21]
	v_mfma_f32_16x16x32_f16 v[10:13], v[184:187], v[220:223], v[10:13]
	v_mfma_f32_16x16x32_f16 v[70:73], v[188:191], v[208:211], v[70:73]
	v_mfma_f32_16x16x32_f16 v[62:65], v[192:195], v[208:211], v[62:65]
	v_mfma_f32_16x16x32_f16 v[50:53], v[188:191], v[212:215], v[50:53]
	v_mfma_f32_16x16x32_f16 v[42:45], v[192:195], v[212:215], v[42:45]
	v_mfma_f32_16x16x32_f16 v[34:37], v[188:191], v[224:227], v[34:37]
	v_mfma_f32_16x16x32_f16 v[26:29], v[192:195], v[224:227], v[26:29]
	v_mfma_f32_16x16x32_f16 v[18:21], v[188:191], v[228:231], v[18:21]
	v_mfma_f32_16x16x32_f16 v[10:13], v[192:195], v[228:231], v[10:13]
	s_setprio 0
	s_barrier
	s_branch .Lc0s_tail
.LBB0_142:
	s_cmp_eq_u32 s61, -2
	s_cbranch_scc1 .Lc0s_first
	s_cmp_eq_u32 s61, 28
	s_cbranch_scc0 .Lc0s_norm
	s_cmp_eq_u64 s[4:5], 0
	s_cbranch_scc1 .Lc0s_final
.Lc0s_norm:
	s_add_i32 s62, s58, 0xfff80080
	s_and_b64 s[10:11], s[10:11], exec
	s_cselect_b32 s78, s54, s62
	s_cselect_b32 s62, s55, s60
	s_add_i32 s10, 0, 0x10000
	v_add_u32_e32 v0, s10, v157
	v_add_u32_e32 v147, s10, v158
	s_add_i32 s10, 0, 0x14000
	ds_read_b128 v[164:167], v0
	ds_read_b128 v[168:171], v0 offset:2048
	ds_read_b128 v[172:175], v147
	ds_read_b128 v[176:179], v147 offset:2048
	v_add_u32_e32 v0, s10, v157
	v_add_u32_e32 v147, s10, v158
	ds_read_b128 v[180:183], v0
	ds_read_b128 v[184:187], v0 offset:2048
	ds_read_b128 v[188:191], v147
	ds_read_b128 v[192:195], v147 offset:2048
	s_or_b32 s64, s78, 0x80
	s_or_b32 s65, s62, 0x80
	s_mov_b32 m0, s41
	ds_read_b128 v[196:199], v161
	ds_read_b128 v[204:207], v161 offset:2048
	ds_read_b128 v[208:211], v162
	ds_read_b128 v[212:215], v162 offset:2048
	ds_read_b128 v[216:219], v161 offset:4096
	ds_read_b128 v[220:223], v161 offset:6144
	ds_read_b128 v[224:227], v162 offset:4096
	ds_read_b128 v[228:231], v162 offset:6144
	buffer_load_dwordx4 v153, s[48:51], s58 offen lds
	s_mov_b32 m0, s42
	s_nop 0
	buffer_load_dwordx4 v155, s[48:51], s58 offen lds
	s_waitcnt vmcnt(8)
	s_waitcnt lgkmcnt(0)
	s_barrier
	s_setprio 1
	s_waitcnt lgkmcnt(0)
	v_mfma_f32_16x16x32_f16 v[118:121], v[164:167], v[196:199], v[118:121]
	v_mfma_f32_16x16x32_f16 v[110:113], v[168:171], v[196:199], v[110:113]
	v_mfma_f32_16x16x32_f16 v[102:105], v[164:167], v[204:207], v[102:105]
	v_mfma_f32_16x16x32_f16 v[94:97], v[168:171], v[204:207], v[94:97]
	v_mfma_f32_16x16x32_f16 v[86:89], v[164:167], v[216:219], v[86:89]
	v_mfma_f32_16x16x32_f16 v[78:81], v[168:171], v[216:219], v[78:81]
	v_mfma_f32_16x16x32_f16 v[66:69], v[164:167], v[220:223], v[66:69]
	v_mfma_f32_16x16x32_f16 v[58:61], v[168:171], v[220:223], v[58:61]
	v_mfma_f32_16x16x32_f16 v[118:121], v[172:175], v[208:211], v[118:121]
	v_mfma_f32_16x16x32_f16 v[110:113], v[176:179], v[208:211], v[110:113]
	v_mfma_f32_16x16x32_f16 v[102:105], v[172:175], v[212:215], v[102:105]
	v_mfma_f32_16x16x32_f16 v[94:97], v[176:179], v[212:215], v[94:97]
	v_mfma_f32_16x16x32_f16 v[86:89], v[172:175], v[224:227], v[86:89]
	v_mfma_f32_16x16x32_f16 v[78:81], v[176:179], v[224:227], v[78:81]
	v_mfma_f32_16x16x32_f16 v[66:69], v[172:175], v[228:231], v[66:69]
	v_mfma_f32_16x16x32_f16 v[58:61], v[176:179], v[228:231], v[58:61]
	s_setprio 0
	s_setprio 1
	v_mfma_f32_16x16x32_f16 v[126:129], v[180:183], v[196:199], v[126:129]
	v_mfma_f32_16x16x32_f16 v[122:125], v[184:187], v[196:199], v[122:125]
	v_mfma_f32_16x16x32_f16 v[114:117], v[180:183], v[204:207], v[114:117]
	v_mfma_f32_16x16x32_f16 v[106:109], v[184:187], v[204:207], v[106:109]
	v_mfma_f32_16x16x32_f16 v[98:101], v[180:183], v[216:219], v[98:101]
	v_mfma_f32_16x16x32_f16 v[90:93], v[184:187], v[216:219], v[90:93]
	v_mfma_f32_16x16x32_f16 v[82:85], v[180:183], v[220:223], v[82:85]
	v_mfma_f32_16x16x32_f16 v[74:77], v[184:187], v[220:223], v[74:77]
	v_mfma_f32_16x16x32_f16 v[126:129], v[188:191], v[208:211], v[126:129]
	v_mfma_f32_16x16x32_f16 v[122:125], v[192:195], v[208:211], v[122:125]
	v_mfma_f32_16x16x32_f16 v[114:117], v[188:191], v[212:215], v[114:117]
	v_mfma_f32_16x16x32_f16 v[106:109], v[192:195], v[212:215], v[106:109]
	v_mfma_f32_16x16x32_f16 v[98:101], v[188:191], v[224:227], v[98:101]
	v_mfma_f32_16x16x32_f16 v[90:93], v[192:195], v[224:227], v[90:93]
	v_mfma_f32_16x16x32_f16 v[82:85], v[188:191], v[228:231], v[82:85]
	v_mfma_f32_16x16x32_f16 v[74:77], v[192:195], v[228:231], v[74:77]
	s_setprio 0
	s_barrier
	s_mov_b32 m0, s26
	s_mov_b32 s10, s50
	s_mov_b32 s11, s51
	ds_read_b128 v[196:199], v161 offset:16384
	ds_read_b128 v[204:207], v161 offset:18432
	ds_read_b128 v[208:211], v162 offset:16384
	ds_read_b128 v[212:215], v162 offset:18432
	ds_read_b128 v[216:219], v161 offset:20480
	ds_read_b128 v[220:223], v161 offset:22528
	ds_read_b128 v[224:227], v162 offset:20480
	ds_read_b128 v[228:231], v162 offset:22528
	buffer_load_dwordx4 v154, s[8:11], s62 offen lds
	s_mov_b32 m0, s27
	s_add_i32 s81, s62, 0x80000
	buffer_load_dwordx4 v156, s[8:11], s62 offen lds
	s_mov_b32 m0, s28
	s_nop 0
	buffer_load_dwordx4 v154, s[8:11], s81 offen lds
	s_mov_b32 m0, s29
	s_nop 0
	buffer_load_dwordx4 v156, s[8:11], s81 offen lds
	s_mov_b32 m0, s3
	s_nop 0
	buffer_load_dwordx4 v153, s[48:51], s78 offen lds
	s_mov_b32 m0, s30
	s_nop 0
	buffer_load_dwordx4 v155, s[48:51], s78 offen lds
	s_waitcnt vmcnt(8)
	s_waitcnt lgkmcnt(0)
	s_barrier
	s_setprio 1
	s_waitcnt lgkmcnt(0)
	v_mfma_f32_16x16x32_f16 v[54:57], v[164:167], v[196:199], v[54:57]
	v_mfma_f32_16x16x32_f16 v[46:49], v[168:171], v[196:199], v[46:49]
	v_mfma_f32_16x16x32_f16 v[38:41], v[164:167], v[204:207], v[38:41]
	v_mfma_f32_16x16x32_f16 v[30:33], v[168:171], v[204:207], v[30:33]
	v_mfma_f32_16x16x32_f16 v[22:25], v[164:167], v[216:219], v[22:25]
	v_mfma_f32_16x16x32_f16 v[14:17], v[168:171], v[216:219], v[14:17]
	v_mfma_f32_16x16x32_f16 v[6:9], v[164:167], v[220:223], v[6:9]
	v_mfma_f32_16x16x32_f16 v[2:5], v[168:171], v[220:223], v[2:5]
	v_mfma_f32_16x16x32_f16 v[54:57], v[172:175], v[208:211], v[54:57]
	v_mfma_f32_16x16x32_f16 v[46:49], v[176:179], v[208:211], v[46:49]
	v_mfma_f32_16x16x32_f16 v[38:41], v[172:175], v[212:215], v[38:41]
	v_mfma_f32_16x16x32_f16 v[30:33], v[176:179], v[212:215], v[30:33]
	v_mfma_f32_16x16x32_f16 v[22:25], v[172:175], v[224:227], v[22:25]
	v_mfma_f32_16x16x32_f16 v[14:17], v[176:179], v[224:227], v[14:17]
	v_mfma_f32_16x16x32_f16 v[6:9], v[172:175], v[228:231], v[6:9]
	v_mfma_f32_16x16x32_f16 v[2:5], v[176:179], v[228:231], v[2:5]
	s_setprio 0
	s_setprio 1
	v_mfma_f32_16x16x32_f16 v[70:73], v[180:183], v[196:199], v[70:73]
	v_mfma_f32_16x16x32_f16 v[62:65], v[184:187], v[196:199], v[62:65]
	v_mfma_f32_16x16x32_f16 v[50:53], v[180:183], v[204:207], v[50:53]
	v_mfma_f32_16x16x32_f16 v[42:45], v[184:187], v[204:207], v[42:45]
	v_mfma_f32_16x16x32_f16 v[34:37], v[180:183], v[216:219], v[34:37]
	v_mfma_f32_16x16x32_f16 v[26:29], v[184:187], v[216:219], v[26:29]
	v_mfma_f32_16x16x32_f16 v[18:21], v[180:183], v[220:223], v[18:21]
	v_mfma_f32_16x16x32_f16 v[10:13], v[184:187], v[220:223], v[10:13]
	v_mfma_f32_16x16x32_f16 v[70:73], v[188:191], v[208:211], v[70:73]
	v_mfma_f32_16x16x32_f16 v[62:65], v[192:195], v[208:211], v[62:65]
	v_mfma_f32_16x16x32_f16 v[50:53], v[188:191], v[212:215], v[50:53]
	v_mfma_f32_16x16x32_f16 v[42:45], v[192:195], v[212:215], v[42:45]
	v_mfma_f32_16x16x32_f16 v[34:37], v[188:191], v[224:227], v[34:37]
	v_mfma_f32_16x16x32_f16 v[26:29], v[192:195], v[224:227], v[26:29]
	v_mfma_f32_16x16x32_f16 v[18:21], v[188:191], v[228:231], v[18:21]
	v_mfma_f32_16x16x32_f16 v[10:13], v[192:195], v[228:231], v[10:13]
	s_setprio 0
	s_barrier
	s_add_i32 s81, 0, 0x18000
	v_add_u32_e32 v0, s81, v157
	v_add_u32_e32 v147, s81, v158
	s_add_i32 s81, 0, 0x1c000
	ds_read_b128 v[164:167], v0
	ds_read_b128 v[168:171], v0 offset:2048
	ds_read_b128 v[172:175], v147
	ds_read_b128 v[176:179], v147 offset:2048
	v_add_u32_e32 v0, s81, v157
	v_add_u32_e32 v147, s81, v158
	ds_read_b128 v[180:183], v0
	ds_read_b128 v[184:187], v0 offset:2048
	ds_read_b128 v[188:191], v147
	ds_read_b128 v[192:195], v147 offset:2048
	s_add_i32 s78, s78, 0x80000
	s_mov_b32 m0, s31
	ds_read_b128 v[196:199], v161 offset:32768
	ds_read_b128 v[204:207], v161 offset:34816
	ds_read_b128 v[208:211], v162 offset:32768
	ds_read_b128 v[212:215], v162 offset:34816
	ds_read_b128 v[216:219], v161 offset:36864
	ds_read_b128 v[220:223], v161 offset:38912
	ds_read_b128 v[224:227], v162 offset:36864
	ds_read_b128 v[228:231], v162 offset:38912
	buffer_load_dwordx4 v153, s[48:51], s78 offen lds
	s_mov_b32 m0, s34
	s_nop 0
	buffer_load_dwordx4 v155, s[48:51], s78 offen lds
	s_waitcnt vmcnt(8)
	s_waitcnt lgkmcnt(0)
	s_barrier
	s_setprio 1
	s_waitcnt lgkmcnt(0)
	v_mfma_f32_16x16x32_f16 v[118:121], v[164:167], v[196:199], v[118:121]
	v_mfma_f32_16x16x32_f16 v[110:113], v[168:171], v[196:199], v[110:113]
	v_mfma_f32_16x16x32_f16 v[102:105], v[164:167], v[204:207], v[102:105]
	v_mfma_f32_16x16x32_f16 v[94:97], v[168:171], v[204:207], v[94:97]
	v_mfma_f32_16x16x32_f16 v[86:89], v[164:167], v[216:219], v[86:89]
	v_mfma_f32_16x16x32_f16 v[78:81], v[168:171], v[216:219], v[78:81]
	v_mfma_f32_16x16x32_f16 v[66:69], v[164:167], v[220:223], v[66:69]
	v_mfma_f32_16x16x32_f16 v[58:61], v[168:171], v[220:223], v[58:61]
	v_mfma_f32_16x16x32_f16 v[118:121], v[172:175], v[208:211], v[118:121]
	v_mfma_f32_16x16x32_f16 v[110:113], v[176:179], v[208:211], v[110:113]
	v_mfma_f32_16x16x32_f16 v[102:105], v[172:175], v[212:215], v[102:105]
	v_mfma_f32_16x16x32_f16 v[94:97], v[176:179], v[212:215], v[94:97]
	v_mfma_f32_16x16x32_f16 v[86:89], v[172:175], v[224:227], v[86:89]
	v_mfma_f32_16x16x32_f16 v[78:81], v[176:179], v[224:227], v[78:81]
	v_mfma_f32_16x16x32_f16 v[66:69], v[172:175], v[228:231], v[66:69]
	v_mfma_f32_16x16x32_f16 v[58:61], v[176:179], v[228:231], v[58:61]
	s_setprio 0
	s_setprio 1
	v_mfma_f32_16x16x32_f16 v[126:129], v[180:183], v[196:199], v[126:129]
	v_mfma_f32_16x16x32_f16 v[122:125], v[184:187], v[196:199], v[122:125]
	v_mfma_f32_16x16x32_f16 v[114:117], v[180:183], v[204:207], v[114:117]
	v_mfma_f32_16x16x32_f16 v[106:109], v[184:187], v[204:207], v[106:109]
	v_mfma_f32_16x16x32_f16 v[98:101], v[180:183], v[216:219], v[98:101]
	v_mfma_f32_16x16x32_f16 v[90:93], v[184:187], v[216:219], v[90:93]
	v_mfma_f32_16x16x32_f16 v[82:85], v[180:183], v[220:223], v[82:85]
	v_mfma_f32_16x16x32_f16 v[74:77], v[184:187], v[220:223], v[74:77]
	v_mfma_f32_16x16x32_f16 v[126:129], v[188:191], v[208:211], v[126:129]
	v_mfma_f32_16x16x32_f16 v[122:125], v[192:195], v[208:211], v[122:125]
	v_mfma_f32_16x16x32_f16 v[114:117], v[188:191], v[212:215], v[114:117]
	v_mfma_f32_16x16x32_f16 v[106:109], v[192:195], v[212:215], v[106:109]
	v_mfma_f32_16x16x32_f16 v[98:101], v[188:191], v[224:227], v[98:101]
	v_mfma_f32_16x16x32_f16 v[90:93], v[192:195], v[224:227], v[90:93]
	v_mfma_f32_16x16x32_f16 v[82:85], v[188:191], v[228:231], v[82:85]
	v_mfma_f32_16x16x32_f16 v[74:77], v[192:195], v[228:231], v[74:77]
	s_setprio 0
	s_barrier
	s_mov_b32 m0, s35
	ds_read_b128 v[196:199], v161 offset:49152
	ds_read_b128 v[204:207], v161 offset:51200
	ds_read_b128 v[208:211], v162 offset:49152
	ds_read_b128 v[212:215], v162 offset:51200
	ds_read_b128 v[216:219], v161 offset:53248
	ds_read_b128 v[220:223], v161 offset:55296
	ds_read_b128 v[224:227], v162 offset:53248
	ds_read_b128 v[228:231], v162 offset:55296
	buffer_load_dwordx4 v154, s[8:11], s65 offen lds
	s_mov_b32 m0, s36
	s_add_i32 s62, s62, 0x80080
	buffer_load_dwordx4 v156, s[8:11], s65 offen lds
	s_mov_b32 m0, s39
	s_nop 0
	buffer_load_dwordx4 v154, s[8:11], s62 offen lds
	s_mov_b32 m0, s40
	s_nop 0
	buffer_load_dwordx4 v156, s[8:11], s62 offen lds
	s_mov_b32 m0, s37
	s_nop 0
	buffer_load_dwordx4 v153, s[48:51], s64 offen lds
	s_mov_b32 m0, s38
	s_nop 0
	buffer_load_dwordx4 v155, s[48:51], s64 offen lds
	s_waitcnt vmcnt(8)
	s_waitcnt lgkmcnt(0)
	s_barrier
	s_setprio 1
	s_waitcnt lgkmcnt(0)
	v_mfma_f32_16x16x32_f16 v[54:57], v[164:167], v[196:199], v[54:57]
	v_mfma_f32_16x16x32_f16 v[46:49], v[168:171], v[196:199], v[46:49]
	v_mfma_f32_16x16x32_f16 v[38:41], v[164:167], v[204:207], v[38:41]
	v_mfma_f32_16x16x32_f16 v[30:33], v[168:171], v[204:207], v[30:33]
	v_mfma_f32_16x16x32_f16 v[22:25], v[164:167], v[216:219], v[22:25]
	v_mfma_f32_16x16x32_f16 v[14:17], v[168:171], v[216:219], v[14:17]
	v_mfma_f32_16x16x32_f16 v[6:9], v[164:167], v[220:223], v[6:9]
	v_mfma_f32_16x16x32_f16 v[2:5], v[168:171], v[220:223], v[2:5]
	v_mfma_f32_16x16x32_f16 v[54:57], v[172:175], v[208:211], v[54:57]
	v_mfma_f32_16x16x32_f16 v[46:49], v[176:179], v[208:211], v[46:49]
	v_mfma_f32_16x16x32_f16 v[38:41], v[172:175], v[212:215], v[38:41]
	v_mfma_f32_16x16x32_f16 v[30:33], v[176:179], v[212:215], v[30:33]
	v_mfma_f32_16x16x32_f16 v[22:25], v[172:175], v[224:227], v[22:25]
	v_mfma_f32_16x16x32_f16 v[14:17], v[176:179], v[224:227], v[14:17]
	v_mfma_f32_16x16x32_f16 v[6:9], v[172:175], v[228:231], v[6:9]
	v_mfma_f32_16x16x32_f16 v[2:5], v[176:179], v[228:231], v[2:5]
	s_setprio 0
	s_setprio 1
	v_mfma_f32_16x16x32_f16 v[70:73], v[180:183], v[196:199], v[70:73]
	v_mfma_f32_16x16x32_f16 v[62:65], v[184:187], v[196:199], v[62:65]
	v_mfma_f32_16x16x32_f16 v[50:53], v[180:183], v[204:207], v[50:53]
	v_mfma_f32_16x16x32_f16 v[42:45], v[184:187], v[204:207], v[42:45]
	v_mfma_f32_16x16x32_f16 v[34:37], v[180:183], v[216:219], v[34:37]
	v_mfma_f32_16x16x32_f16 v[26:29], v[184:187], v[216:219], v[26:29]
	v_mfma_f32_16x16x32_f16 v[18:21], v[180:183], v[220:223], v[18:21]
	v_mfma_f32_16x16x32_f16 v[10:13], v[184:187], v[220:223], v[10:13]
	v_mfma_f32_16x16x32_f16 v[70:73], v[188:191], v[208:211], v[70:73]
	v_mfma_f32_16x16x32_f16 v[62:65], v[192:195], v[208:211], v[62:65]
	v_mfma_f32_16x16x32_f16 v[50:53], v[188:191], v[212:215], v[50:53]
	v_mfma_f32_16x16x32_f16 v[42:45], v[192:195], v[212:215], v[42:45]
	v_mfma_f32_16x16x32_f16 v[34:37], v[188:191], v[224:227], v[34:37]
	v_mfma_f32_16x16x32_f16 v[26:29], v[192:195], v[224:227], v[26:29]
	v_mfma_f32_16x16x32_f16 v[18:21], v[188:191], v[228:231], v[18:21]
	v_mfma_f32_16x16x32_f16 v[10:13], v[192:195], v[228:231], v[10:13]
	s_setprio 0
	s_barrier

.Lc0b_final:
	s_add_i32 s55, s52, 0xfff80080
	s_and_b64 s[10:11], s[10:11], exec
	s_cselect_b32 s60, s46, s55
	s_cselect_b32 s55, s47, s53
	s_add_i32 s10, 0, 0x10000
	v_add_u32_e32 v0, s10, v157
	v_add_u32_e32 v147, s10, v158
	s_add_i32 s10, 0, 0x14000
	ds_read_b128 v[164:167], v0
	ds_read_b128 v[168:171], v0 offset:2048
	ds_read_b128 v[172:175], v147
	ds_read_b128 v[176:179], v147 offset:2048
	v_add_u32_e32 v0, s10, v157
	v_add_u32_e32 v147, s10, v158
	ds_read_b128 v[180:183], v0
	ds_read_b128 v[184:187], v0 offset:2048
	ds_read_b128 v[188:191], v147
	ds_read_b128 v[192:195], v147 offset:2048
	s_or_b32 s56, s60, 0x80
	s_or_b32 s58, s55, 0x80
	s_mov_b32 m0, s37
	ds_read_b128 v[196:199], v161
	ds_read_b128 v[204:207], v161 offset:2048
	ds_read_b128 v[208:211], v162
	ds_read_b128 v[212:215], v162 offset:2048
	ds_read_b128 v[216:219], v161 offset:4096
	ds_read_b128 v[220:223], v161 offset:6144
	ds_read_b128 v[224:227], v162 offset:4096
	ds_read_b128 v[228:231], v162 offset:6144
	buffer_load_dwordx4 v151, s[48:51], s52 offen lds
	s_mov_b32 m0, s38
	s_nop 0
	buffer_load_dwordx4 v155, s[48:51], s52 offen lds
	s_waitcnt vmcnt(8)
	s_waitcnt lgkmcnt(0)
	s_barrier
	s_setprio 1
	s_waitcnt lgkmcnt(0)
	v_mfma_f32_16x16x32_f16 v[94:97], v[164:167], v[196:199], v[94:97]
	v_mfma_f32_16x16x32_f16 v[98:101], v[168:171], v[196:199], v[98:101]
	v_mfma_f32_16x16x32_f16 v[62:65], v[164:167], v[204:207], v[62:65]
	v_mfma_f32_16x16x32_f16 v[74:77], v[168:171], v[204:207], v[74:77]
	v_mfma_f32_16x16x32_f16 v[34:37], v[164:167], v[216:219], v[34:37]
	v_mfma_f32_16x16x32_f16 v[42:45], v[168:171], v[216:219], v[42:45]
	v_mfma_f32_16x16x32_f16 v[14:17], v[164:167], v[220:223], v[14:17]
	v_mfma_f32_16x16x32_f16 v[22:25], v[168:171], v[220:223], v[22:25]
	v_mfma_f32_16x16x32_f16 v[94:97], v[172:175], v[208:211], v[94:97]
	v_mfma_f32_16x16x32_f16 v[98:101], v[176:179], v[208:211], v[98:101]
	v_mfma_f32_16x16x32_f16 v[62:65], v[172:175], v[212:215], v[62:65]
	v_mfma_f32_16x16x32_f16 v[74:77], v[176:179], v[212:215], v[74:77]
	v_mfma_f32_16x16x32_f16 v[34:37], v[172:175], v[224:227], v[34:37]
	v_mfma_f32_16x16x32_f16 v[42:45], v[176:179], v[224:227], v[42:45]
	v_mfma_f32_16x16x32_f16 v[14:17], v[172:175], v[228:231], v[14:17]
	v_mfma_f32_16x16x32_f16 v[22:25], v[176:179], v[228:231], v[22:25]
	s_setprio 0
	s_setprio 1
	v_mfma_f32_16x16x32_f16 v[122:125], v[180:183], v[196:199], v[122:125]
	v_mfma_f32_16x16x32_f16 v[126:129], v[184:187], v[196:199], v[126:129]
	v_mfma_f32_16x16x32_f16 v[110:113], v[180:183], v[204:207], v[110:113]
	v_mfma_f32_16x16x32_f16 v[118:121], v[184:187], v[204:207], v[118:121]
	v_mfma_f32_16x16x32_f16 v[86:89], v[180:183], v[216:219], v[86:89]
	v_mfma_f32_16x16x32_f16 v[102:105], v[184:187], v[216:219], v[102:105]
	v_mfma_f32_16x16x32_f16 v[70:73], v[180:183], v[220:223], v[70:73]
	v_mfma_f32_16x16x32_f16 v[78:81], v[184:187], v[220:223], v[78:81]
	v_mfma_f32_16x16x32_f16 v[122:125], v[188:191], v[208:211], v[122:125]
	v_mfma_f32_16x16x32_f16 v[126:129], v[192:195], v[208:211], v[126:129]
	v_mfma_f32_16x16x32_f16 v[110:113], v[188:191], v[212:215], v[110:113]
	v_mfma_f32_16x16x32_f16 v[118:121], v[192:195], v[212:215], v[118:121]
	v_mfma_f32_16x16x32_f16 v[86:89], v[188:191], v[224:227], v[86:89]
	v_mfma_f32_16x16x32_f16 v[102:105], v[192:195], v[224:227], v[102:105]
	v_mfma_f32_16x16x32_f16 v[70:73], v[188:191], v[228:231], v[70:73]
	v_mfma_f32_16x16x32_f16 v[78:81], v[192:195], v[228:231], v[78:81]
	s_setprio 0
	s_barrier
	s_mov_b32 s10, s50
	s_mov_b32 s11, s51
	ds_read_b128 v[196:199], v161 offset:16384
	ds_read_b128 v[204:207], v161 offset:18432
	ds_read_b128 v[208:211], v162 offset:16384
	ds_read_b128 v[212:215], v162 offset:18432
	ds_read_b128 v[216:219], v161 offset:20480
	ds_read_b128 v[220:223], v161 offset:22528
	ds_read_b128 v[224:227], v162 offset:20480
	ds_read_b128 v[228:231], v162 offset:22528
	s_add_i32 s61, s55, 0x80000
	s_waitcnt vmcnt(2)
	s_waitcnt lgkmcnt(0)
	s_barrier
	s_setprio 1
	s_waitcnt lgkmcnt(0)
	v_mfma_f32_16x16x32_f16 v[54:57], v[164:167], v[196:199], v[54:57]
	v_mfma_f32_16x16x32_f16 v[66:69], v[168:171], v[196:199], v[66:69]
	v_mfma_f32_16x16x32_f16 v[30:33], v[164:167], v[204:207], v[30:33]
	v_mfma_f32_16x16x32_f16 v[38:41], v[168:171], v[204:207], v[38:41]
	v_mfma_f32_16x16x32_f16 v[10:13], v[164:167], v[216:219], v[10:13]
	v_mfma_f32_16x16x32_f16 v[18:21], v[168:171], v[216:219], v[18:21]
	v_mfma_f32_16x16x32_f16 v[2:5], v[164:167], v[220:223], v[2:5]
	v_mfma_f32_16x16x32_f16 v[6:9], v[168:171], v[220:223], v[6:9]
	v_mfma_f32_16x16x32_f16 v[54:57], v[172:175], v[208:211], v[54:57]
	v_mfma_f32_16x16x32_f16 v[66:69], v[176:179], v[208:211], v[66:69]
	v_mfma_f32_16x16x32_f16 v[30:33], v[172:175], v[212:215], v[30:33]
	v_mfma_f32_16x16x32_f16 v[38:41], v[176:179], v[212:215], v[38:41]
	v_mfma_f32_16x16x32_f16 v[10:13], v[172:175], v[224:227], v[10:13]
	v_mfma_f32_16x16x32_f16 v[18:21], v[176:179], v[224:227], v[18:21]
	v_mfma_f32_16x16x32_f16 v[2:5], v[172:175], v[228:231], v[2:5]
	v_mfma_f32_16x16x32_f16 v[6:9], v[176:179], v[228:231], v[6:9]
	s_setprio 0
	s_setprio 1
	v_mfma_f32_16x16x32_f16 v[106:109], v[180:183], v[196:199], v[106:109]
	v_mfma_f32_16x16x32_f16 v[114:117], v[184:187], v[196:199], v[114:117]
	v_mfma_f32_16x16x32_f16 v[82:85], v[180:183], v[204:207], v[82:85]
	v_mfma_f32_16x16x32_f16 v[90:93], v[184:187], v[204:207], v[90:93]
	v_mfma_f32_16x16x32_f16 v[46:49], v[180:183], v[216:219], v[46:49]
	v_mfma_f32_16x16x32_f16 v[58:61], v[184:187], v[216:219], v[58:61]
	v_mfma_f32_16x16x32_f16 v[26:29], v[180:183], v[220:223], v[26:29]
	v_mfma_f32_16x16x32_f16 v[50:53], v[184:187], v[220:223], v[50:53]
	v_mfma_f32_16x16x32_f16 v[106:109], v[188:191], v[208:211], v[106:109]
	v_mfma_f32_16x16x32_f16 v[114:117], v[192:195], v[208:211], v[114:117]
	v_mfma_f32_16x16x32_f16 v[82:85], v[188:191], v[212:215], v[82:85]
	v_mfma_f32_16x16x32_f16 v[90:93], v[192:195], v[212:215], v[90:93]
	v_mfma_f32_16x16x32_f16 v[46:49], v[188:191], v[224:227], v[46:49]
	v_mfma_f32_16x16x32_f16 v[58:61], v[192:195], v[224:227], v[58:61]
	v_mfma_f32_16x16x32_f16 v[26:29], v[188:191], v[228:231], v[26:29]
	v_mfma_f32_16x16x32_f16 v[50:53], v[192:195], v[228:231], v[50:53]
	s_setprio 0
	s_barrier
	s_add_i32 s61, 0, 0x18000
	v_add_u32_e32 v0, s61, v157
	v_add_u32_e32 v147, s61, v158
	s_add_i32 s61, 0, 0x1c000
	ds_read_b128 v[164:167], v0
	ds_read_b128 v[168:171], v0 offset:2048
	ds_read_b128 v[172:175], v147
	ds_read_b128 v[176:179], v147 offset:2048
	v_add_u32_e32 v0, s61, v157
	v_add_u32_e32 v147, s61, v158
	ds_read_b128 v[180:183], v0
	ds_read_b128 v[184:187], v0 offset:2048
	ds_read_b128 v[188:191], v147
	ds_read_b128 v[192:195], v147 offset:2048
	s_add_i32 s60, s60, 0x80000
	ds_read_b128 v[196:199], v161 offset:32768
	ds_read_b128 v[204:207], v161 offset:34816
	ds_read_b128 v[208:211], v162 offset:32768
	ds_read_b128 v[212:215], v162 offset:34816
	ds_read_b128 v[216:219], v161 offset:36864
	ds_read_b128 v[220:223], v161 offset:38912
	ds_read_b128 v[224:227], v162 offset:36864
	ds_read_b128 v[228:231], v162 offset:38912
	s_waitcnt vmcnt(0)
	s_waitcnt lgkmcnt(0)
	s_barrier
	s_setprio 1
	s_waitcnt lgkmcnt(0)
	v_mfma_f32_16x16x32_f16 v[94:97], v[164:167], v[196:199], v[94:97]
	v_mfma_f32_16x16x32_f16 v[98:101], v[168:171], v[196:199], v[98:101]
	v_mfma_f32_16x16x32_f16 v[62:65], v[164:167], v[204:207], v[62:65]
	v_mfma_f32_16x16x32_f16 v[74:77], v[168:171], v[204:207], v[74:77]
	v_mfma_f32_16x16x32_f16 v[34:37], v[164:167], v[216:219], v[34:37]
	v_mfma_f32_16x16x32_f16 v[42:45], v[168:171], v[216:219], v[42:45]
	v_mfma_f32_16x16x32_f16 v[14:17], v[164:167], v[220:223], v[14:17]
	v_mfma_f32_16x16x32_f16 v[22:25], v[168:171], v[220:223], v[22:25]
	v_mfma_f32_16x16x32_f16 v[94:97], v[172:175], v[208:211], v[94:97]
	v_mfma_f32_16x16x32_f16 v[98:101], v[176:179], v[208:211], v[98:101]
	v_mfma_f32_16x16x32_f16 v[62:65], v[172:175], v[212:215], v[62:65]
	v_mfma_f32_16x16x32_f16 v[74:77], v[176:179], v[212:215], v[74:77]
	v_mfma_f32_16x16x32_f16 v[34:37], v[172:175], v[224:227], v[34:37]
	v_mfma_f32_16x16x32_f16 v[42:45], v[176:179], v[224:227], v[42:45]
	v_mfma_f32_16x16x32_f16 v[14:17], v[172:175], v[228:231], v[14:17]
	v_mfma_f32_16x16x32_f16 v[22:25], v[176:179], v[228:231], v[22:25]
	s_setprio 0
	s_setprio 1
	v_mfma_f32_16x16x32_f16 v[122:125], v[180:183], v[196:199], v[122:125]
	v_mfma_f32_16x16x32_f16 v[126:129], v[184:187], v[196:199], v[126:129]
	v_mfma_f32_16x16x32_f16 v[110:113], v[180:183], v[204:207], v[110:113]
	v_mfma_f32_16x16x32_f16 v[118:121], v[184:187], v[204:207], v[118:121]
	v_mfma_f32_16x16x32_f16 v[86:89], v[180:183], v[216:219], v[86:89]
	v_mfma_f32_16x16x32_f16 v[102:105], v[184:187], v[216:219], v[102:105]
	v_mfma_f32_16x16x32_f16 v[70:73], v[180:183], v[220:223], v[70:73]
	v_mfma_f32_16x16x32_f16 v[78:81], v[184:187], v[220:223], v[78:81]
	v_mfma_f32_16x16x32_f16 v[122:125], v[188:191], v[208:211], v[122:125]
	v_mfma_f32_16x16x32_f16 v[126:129], v[192:195], v[208:211], v[126:129]
	v_mfma_f32_16x16x32_f16 v[110:113], v[188:191], v[212:215], v[110:113]
	v_mfma_f32_16x16x32_f16 v[118:121], v[192:195], v[212:215], v[118:121]
	v_mfma_f32_16x16x32_f16 v[86:89], v[188:191], v[224:227], v[86:89]
	v_mfma_f32_16x16x32_f16 v[102:105], v[192:195], v[224:227], v[102:105]
	v_mfma_f32_16x16x32_f16 v[70:73], v[188:191], v[228:231], v[70:73]
	v_mfma_f32_16x16x32_f16 v[78:81], v[192:195], v[228:231], v[78:81]
	s_setprio 0
	s_barrier
	ds_read_b128 v[196:199], v161 offset:49152
	ds_read_b128 v[204:207], v161 offset:51200
	ds_read_b128 v[208:211], v162 offset:49152
	ds_read_b128 v[212:215], v162 offset:51200
	ds_read_b128 v[216:219], v161 offset:53248
	ds_read_b128 v[220:223], v161 offset:55296
	ds_read_b128 v[224:227], v162 offset:53248
	ds_read_b128 v[228:231], v162 offset:55296
	s_add_i32 s55, s55, 0x80080
	s_waitcnt vmcnt(0)
	s_waitcnt lgkmcnt(0)
	s_barrier
	s_setprio 1
	s_waitcnt lgkmcnt(0)
	v_mfma_f32_16x16x32_f16 v[54:57], v[164:167], v[196:199], v[54:57]
	v_mfma_f32_16x16x32_f16 v[66:69], v[168:171], v[196:199], v[66:69]
	v_mfma_f32_16x16x32_f16 v[30:33], v[164:167], v[204:207], v[30:33]
	v_mfma_f32_16x16x32_f16 v[38:41], v[168:171], v[204:207], v[38:41]
	v_mfma_f32_16x16x32_f16 v[10:13], v[164:167], v[216:219], v[10:13]
	v_mfma_f32_16x16x32_f16 v[18:21], v[168:171], v[216:219], v[18:21]
	v_mfma_f32_16x16x32_f16 v[2:5], v[164:167], v[220:223], v[2:5]
	v_mfma_f32_16x16x32_f16 v[6:9], v[168:171], v[220:223], v[6:9]
	v_mfma_f32_16x16x32_f16 v[54:57], v[172:175], v[208:211], v[54:57]
	v_mfma_f32_16x16x32_f16 v[66:69], v[176:179], v[208:211], v[66:69]
	v_mfma_f32_16x16x32_f16 v[30:33], v[172:175], v[212:215], v[30:33]
	v_mfma_f32_16x16x32_f16 v[38:41], v[176:179], v[212:215], v[38:41]
	v_mfma_f32_16x16x32_f16 v[10:13], v[172:175], v[224:227], v[10:13]
	v_mfma_f32_16x16x32_f16 v[18:21], v[176:179], v[224:227], v[18:21]
	v_mfma_f32_16x16x32_f16 v[2:5], v[172:175], v[228:231], v[2:5]
	v_mfma_f32_16x16x32_f16 v[6:9], v[176:179], v[228:231], v[6:9]
	s_setprio 0
	s_setprio 1
	v_mfma_f32_16x16x32_f16 v[106:109], v[180:183], v[196:199], v[106:109]
	v_mfma_f32_16x16x32_f16 v[114:117], v[184:187], v[196:199], v[114:117]
	v_mfma_f32_16x16x32_f16 v[82:85], v[180:183], v[204:207], v[82:85]
	v_mfma_f32_16x16x32_f16 v[90:93], v[184:187], v[204:207], v[90:93]
	v_mfma_f32_16x16x32_f16 v[46:49], v[180:183], v[216:219], v[46:49]
	v_mfma_f32_16x16x32_f16 v[58:61], v[184:187], v[216:219], v[58:61]
	v_mfma_f32_16x16x32_f16 v[26:29], v[180:183], v[220:223], v[26:29]
	v_mfma_f32_16x16x32_f16 v[50:53], v[184:187], v[220:223], v[50:53]
	v_mfma_f32_16x16x32_f16 v[106:109], v[188:191], v[208:211], v[106:109]
	v_mfma_f32_16x16x32_f16 v[114:117], v[192:195], v[208:211], v[114:117]
	v_mfma_f32_16x16x32_f16 v[82:85], v[188:191], v[212:215], v[82:85]
	v_mfma_f32_16x16x32_f16 v[90:93], v[192:195], v[212:215], v[90:93]
	v_mfma_f32_16x16x32_f16 v[46:49], v[188:191], v[224:227], v[46:49]
	v_mfma_f32_16x16x32_f16 v[58:61], v[192:195], v[224:227], v[58:61]
	v_mfma_f32_16x16x32_f16 v[26:29], v[188:191], v[228:231], v[26:29]
	v_mfma_f32_16x16x32_f16 v[50:53], v[192:195], v[228:231], v[50:53]
	s_setprio 0
	s_barrier
	s_branch .Lc0b_tail
.LBB0_162:
	s_cmp_eq_u32 s54, -2
	s_cbranch_scc1 .Lc0b_first
	s_cmp_eq_u32 s54, 28
	s_cbranch_scc0 .Lc0b_norm
	s_cmp_eq_u64 s[4:5], 0
	s_cbranch_scc1 .Lc0b_final
.Lc0b_norm:
	s_add_i32 s55, s52, 0xfff80080
	s_and_b64 s[10:11], s[10:11], exec
	s_cselect_b32 s60, s46, s55
	s_cselect_b32 s55, s47, s53
	s_add_i32 s10, 0, 0x10000
	v_add_u32_e32 v0, s10, v157
	v_add_u32_e32 v147, s10, v158
	s_add_i32 s10, 0, 0x14000
	ds_read_b128 v[164:167], v0
	ds_read_b128 v[168:171], v0 offset:2048
	ds_read_b128 v[172:175], v147
	ds_read_b128 v[176:179], v147 offset:2048
	v_add_u32_e32 v0, s10, v157
	v_add_u32_e32 v147, s10, v158
	ds_read_b128 v[180:183], v0
	ds_read_b128 v[184:187], v0 offset:2048
	ds_read_b128 v[188:191], v147
	ds_read_b128 v[192:195], v147 offset:2048
	s_or_b32 s56, s60, 0x80
	s_or_b32 s58, s55, 0x80
	s_mov_b32 m0, s37
	ds_read_b128 v[196:199], v161
	ds_read_b128 v[204:207], v161 offset:2048
	ds_read_b128 v[208:211], v162
	ds_read_b128 v[212:215], v162 offset:2048
	ds_read_b128 v[216:219], v161 offset:4096
	ds_read_b128 v[220:223], v161 offset:6144
	ds_read_b128 v[224:227], v162 offset:4096
	ds_read_b128 v[228:231], v162 offset:6144
	buffer_load_dwordx4 v151, s[48:51], s52 offen lds
	s_mov_b32 m0, s38
	s_nop 0
	buffer_load_dwordx4 v155, s[48:51], s52 offen lds
	s_waitcnt vmcnt(8)
	s_waitcnt lgkmcnt(0)
	s_barrier
	s_setprio 1
	s_waitcnt lgkmcnt(0)
	v_mfma_f32_16x16x32_f16 v[94:97], v[164:167], v[196:199], v[94:97]
	v_mfma_f32_16x16x32_f16 v[98:101], v[168:171], v[196:199], v[98:101]
	v_mfma_f32_16x16x32_f16 v[62:65], v[164:167], v[204:207], v[62:65]
	v_mfma_f32_16x16x32_f16 v[74:77], v[168:171], v[204:207], v[74:77]
	v_mfma_f32_16x16x32_f16 v[34:37], v[164:167], v[216:219], v[34:37]
	v_mfma_f32_16x16x32_f16 v[42:45], v[168:171], v[216:219], v[42:45]
	v_mfma_f32_16x16x32_f16 v[14:17], v[164:167], v[220:223], v[14:17]
	v_mfma_f32_16x16x32_f16 v[22:25], v[168:171], v[220:223], v[22:25]
	v_mfma_f32_16x16x32_f16 v[94:97], v[172:175], v[208:211], v[94:97]
	v_mfma_f32_16x16x32_f16 v[98:101], v[176:179], v[208:211], v[98:101]
	v_mfma_f32_16x16x32_f16 v[62:65], v[172:175], v[212:215], v[62:65]
	v_mfma_f32_16x16x32_f16 v[74:77], v[176:179], v[212:215], v[74:77]
	v_mfma_f32_16x16x32_f16 v[34:37], v[172:175], v[224:227], v[34:37]
	v_mfma_f32_16x16x32_f16 v[42:45], v[176:179], v[224:227], v[42:45]
	v_mfma_f32_16x16x32_f16 v[14:17], v[172:175], v[228:231], v[14:17]
	v_mfma_f32_16x16x32_f16 v[22:25], v[176:179], v[228:231], v[22:25]
	s_setprio 0
	s_setprio 1
	v_mfma_f32_16x16x32_f16 v[122:125], v[180:183], v[196:199], v[122:125]
	v_mfma_f32_16x16x32_f16 v[126:129], v[184:187], v[196:199], v[126:129]
	v_mfma_f32_16x16x32_f16 v[110:113], v[180:183], v[204:207], v[110:113]
	v_mfma_f32_16x16x32_f16 v[118:121], v[184:187], v[204:207], v[118:121]
	v_mfma_f32_16x16x32_f16 v[86:89], v[180:183], v[216:219], v[86:89]
	v_mfma_f32_16x16x32_f16 v[102:105], v[184:187], v[216:219], v[102:105]
	v_mfma_f32_16x16x32_f16 v[70:73], v[180:183], v[220:223], v[70:73]
	v_mfma_f32_16x16x32_f16 v[78:81], v[184:187], v[220:223], v[78:81]
	v_mfma_f32_16x16x32_f16 v[122:125], v[188:191], v[208:211], v[122:125]
	v_mfma_f32_16x16x32_f16 v[126:129], v[192:195], v[208:211], v[126:129]
	v_mfma_f32_16x16x32_f16 v[110:113], v[188:191], v[212:215], v[110:113]
	v_mfma_f32_16x16x32_f16 v[118:121], v[192:195], v[212:215], v[118:121]
	v_mfma_f32_16x16x32_f16 v[86:89], v[188:191], v[224:227], v[86:89]
	v_mfma_f32_16x16x32_f16 v[102:105], v[192:195], v[224:227], v[102:105]
	v_mfma_f32_16x16x32_f16 v[70:73], v[188:191], v[228:231], v[70:73]
	v_mfma_f32_16x16x32_f16 v[78:81], v[192:195], v[228:231], v[78:81]
	s_setprio 0
	s_barrier
	s_mov_b32 m0, s2
	s_mov_b32 s10, s50
	s_mov_b32 s11, s51
	ds_read_b128 v[196:199], v161 offset:16384
	ds_read_b128 v[204:207], v161 offset:18432
	ds_read_b128 v[208:211], v162 offset:16384
	ds_read_b128 v[212:215], v162 offset:18432
	ds_read_b128 v[216:219], v161 offset:20480
	ds_read_b128 v[220:223], v161 offset:22528
	ds_read_b128 v[224:227], v162 offset:20480
	ds_read_b128 v[228:231], v162 offset:22528
	buffer_load_dwordx4 v153, s[8:11], s55 offen lds
	s_mov_b32 m0, s3
	s_add_i32 s61, s55, 0x80000
	buffer_load_dwordx4 v156, s[8:11], s55 offen lds
	s_mov_b32 m0, s20
	s_nop 0
	buffer_load_dwordx4 v153, s[8:11], s61 offen lds
	s_mov_b32 m0, s21
	s_nop 0
	buffer_load_dwordx4 v156, s[8:11], s61 offen lds
	s_mov_b32 m0, s1
	s_nop 0
	buffer_load_dwordx4 v151, s[48:51], s60 offen lds
	s_mov_b32 m0, s26
	s_nop 0
	buffer_load_dwordx4 v155, s[48:51], s60 offen lds
	s_waitcnt vmcnt(8)
	s_waitcnt lgkmcnt(0)
	s_barrier
	s_setprio 1
	s_waitcnt lgkmcnt(0)
	v_mfma_f32_16x16x32_f16 v[54:57], v[164:167], v[196:199], v[54:57]
	v_mfma_f32_16x16x32_f16 v[66:69], v[168:171], v[196:199], v[66:69]
	v_mfma_f32_16x16x32_f16 v[30:33], v[164:167], v[204:207], v[30:33]
	v_mfma_f32_16x16x32_f16 v[38:41], v[168:171], v[204:207], v[38:41]
	v_mfma_f32_16x16x32_f16 v[10:13], v[164:167], v[216:219], v[10:13]
	v_mfma_f32_16x16x32_f16 v[18:21], v[168:171], v[216:219], v[18:21]
	v_mfma_f32_16x16x32_f16 v[2:5], v[164:167], v[220:223], v[2:5]
	v_mfma_f32_16x16x32_f16 v[6:9], v[168:171], v[220:223], v[6:9]
	v_mfma_f32_16x16x32_f16 v[54:57], v[172:175], v[208:211], v[54:57]
	v_mfma_f32_16x16x32_f16 v[66:69], v[176:179], v[208:211], v[66:69]
	v_mfma_f32_16x16x32_f16 v[30:33], v[172:175], v[212:215], v[30:33]
	v_mfma_f32_16x16x32_f16 v[38:41], v[176:179], v[212:215], v[38:41]
	v_mfma_f32_16x16x32_f16 v[10:13], v[172:175], v[224:227], v[10:13]
	v_mfma_f32_16x16x32_f16 v[18:21], v[176:179], v[224:227], v[18:21]
	v_mfma_f32_16x16x32_f16 v[2:5], v[172:175], v[228:231], v[2:5]
	v_mfma_f32_16x16x32_f16 v[6:9], v[176:179], v[228:231], v[6:9]
	s_setprio 0
	s_setprio 1
	v_mfma_f32_16x16x32_f16 v[106:109], v[180:183], v[196:199], v[106:109]
	v_mfma_f32_16x16x32_f16 v[114:117], v[184:187], v[196:199], v[114:117]
	v_mfma_f32_16x16x32_f16 v[82:85], v[180:183], v[204:207], v[82:85]
	v_mfma_f32_16x16x32_f16 v[90:93], v[184:187], v[204:207], v[90:93]
	v_mfma_f32_16x16x32_f16 v[46:49], v[180:183], v[216:219], v[46:49]
	v_mfma_f32_16x16x32_f16 v[58:61], v[184:187], v[216:219], v[58:61]
	v_mfma_f32_16x16x32_f16 v[26:29], v[180:183], v[220:223], v[26:29]
	v_mfma_f32_16x16x32_f16 v[50:53], v[184:187], v[220:223], v[50:53]
	v_mfma_f32_16x16x32_f16 v[106:109], v[188:191], v[208:211], v[106:109]
	v_mfma_f32_16x16x32_f16 v[114:117], v[192:195], v[208:211], v[114:117]
	v_mfma_f32_16x16x32_f16 v[82:85], v[188:191], v[212:215], v[82:85]
	v_mfma_f32_16x16x32_f16 v[90:93], v[192:195], v[212:215], v[90:93]
	v_mfma_f32_16x16x32_f16 v[46:49], v[188:191], v[224:227], v[46:49]
	v_mfma_f32_16x16x32_f16 v[58:61], v[192:195], v[224:227], v[58:61]
	v_mfma_f32_16x16x32_f16 v[26:29], v[188:191], v[228:231], v[26:29]
	v_mfma_f32_16x16x32_f16 v[50:53], v[192:195], v[228:231], v[50:53]
	s_setprio 0
	s_barrier
	s_add_i32 s61, 0, 0x18000
	v_add_u32_e32 v0, s61, v157
	v_add_u32_e32 v147, s61, v158
	s_add_i32 s61, 0, 0x1c000
	ds_read_b128 v[164:167], v0
	ds_read_b128 v[168:171], v0 offset:2048
	ds_read_b128 v[172:175], v147
	ds_read_b128 v[176:179], v147 offset:2048
	v_add_u32_e32 v0, s61, v157
	v_add_u32_e32 v147, s61, v158
	ds_read_b128 v[180:183], v0
	ds_read_b128 v[184:187], v0 offset:2048
	ds_read_b128 v[188:191], v147
	ds_read_b128 v[192:195], v147 offset:2048
	s_add_i32 s60, s60, 0x80000
	s_mov_b32 m0, s27
	ds_read_b128 v[196:199], v161 offset:32768
	ds_read_b128 v[204:207], v161 offset:34816
	ds_read_b128 v[208:211], v162 offset:32768
	ds_read_b128 v[212:215], v162 offset:34816
	ds_read_b128 v[216:219], v161 offset:36864
	ds_read_b128 v[220:223], v161 offset:38912
	ds_read_b128 v[224:227], v162 offset:36864
	ds_read_b128 v[228:231], v162 offset:38912
	buffer_load_dwordx4 v151, s[48:51], s60 offen lds
	s_mov_b32 m0, s28
	s_nop 0
	buffer_load_dwordx4 v155, s[48:51], s60 offen lds
	s_waitcnt vmcnt(8)
	s_waitcnt lgkmcnt(0)
	s_barrier
	s_setprio 1
	s_waitcnt lgkmcnt(0)
	v_mfma_f32_16x16x32_f16 v[94:97], v[164:167], v[196:199], v[94:97]
	v_mfma_f32_16x16x32_f16 v[98:101], v[168:171], v[196:199], v[98:101]
	v_mfma_f32_16x16x32_f16 v[62:65], v[164:167], v[204:207], v[62:65]
	v_mfma_f32_16x16x32_f16 v[74:77], v[168:171], v[204:207], v[74:77]
	v_mfma_f32_16x16x32_f16 v[34:37], v[164:167], v[216:219], v[34:37]
	v_mfma_f32_16x16x32_f16 v[42:45], v[168:171], v[216:219], v[42:45]
	v_mfma_f32_16x16x32_f16 v[14:17], v[164:167], v[220:223], v[14:17]
	v_mfma_f32_16x16x32_f16 v[22:25], v[168:171], v[220:223], v[22:25]
	v_mfma_f32_16x16x32_f16 v[94:97], v[172:175], v[208:211], v[94:97]
	v_mfma_f32_16x16x32_f16 v[98:101], v[176:179], v[208:211], v[98:101]
	v_mfma_f32_16x16x32_f16 v[62:65], v[172:175], v[212:215], v[62:65]
	v_mfma_f32_16x16x32_f16 v[74:77], v[176:179], v[212:215], v[74:77]
	v_mfma_f32_16x16x32_f16 v[34:37], v[172:175], v[224:227], v[34:37]
	v_mfma_f32_16x16x32_f16 v[42:45], v[176:179], v[224:227], v[42:45]
	v_mfma_f32_16x16x32_f16 v[14:17], v[172:175], v[228:231], v[14:17]
	v_mfma_f32_16x16x32_f16 v[22:25], v[176:179], v[228:231], v[22:25]
	s_setprio 0
	s_setprio 1
	v_mfma_f32_16x16x32_f16 v[122:125], v[180:183], v[196:199], v[122:125]
	v_mfma_f32_16x16x32_f16 v[126:129], v[184:187], v[196:199], v[126:129]
	v_mfma_f32_16x16x32_f16 v[110:113], v[180:183], v[204:207], v[110:113]
	v_mfma_f32_16x16x32_f16 v[118:121], v[184:187], v[204:207], v[118:121]
	v_mfma_f32_16x16x32_f16 v[86:89], v[180:183], v[216:219], v[86:89]
	v_mfma_f32_16x16x32_f16 v[102:105], v[184:187], v[216:219], v[102:105]
	v_mfma_f32_16x16x32_f16 v[70:73], v[180:183], v[220:223], v[70:73]
	v_mfma_f32_16x16x32_f16 v[78:81], v[184:187], v[220:223], v[78:81]
	v_mfma_f32_16x16x32_f16 v[122:125], v[188:191], v[208:211], v[122:125]
	v_mfma_f32_16x16x32_f16 v[126:129], v[192:195], v[208:211], v[126:129]
	v_mfma_f32_16x16x32_f16 v[110:113], v[188:191], v[212:215], v[110:113]
	v_mfma_f32_16x16x32_f16 v[118:121], v[192:195], v[212:215], v[118:121]
	v_mfma_f32_16x16x32_f16 v[86:89], v[188:191], v[224:227], v[86:89]
	v_mfma_f32_16x16x32_f16 v[102:105], v[192:195], v[224:227], v[102:105]
	v_mfma_f32_16x16x32_f16 v[70:73], v[188:191], v[228:231], v[70:73]
	v_mfma_f32_16x16x32_f16 v[78:81], v[192:195], v[228:231], v[78:81]
	s_setprio 0
	s_barrier
	s_mov_b32 m0, s29
	ds_read_b128 v[196:199], v161 offset:49152
	ds_read_b128 v[204:207], v161 offset:51200
	ds_read_b128 v[208:211], v162 offset:49152
	ds_read_b128 v[212:215], v162 offset:51200
	ds_read_b128 v[216:219], v161 offset:53248
	ds_read_b128 v[220:223], v161 offset:55296
	ds_read_b128 v[224:227], v162 offset:53248
	ds_read_b128 v[228:231], v162 offset:55296
	buffer_load_dwordx4 v153, s[8:11], s58 offen lds
	s_mov_b32 m0, s30
	s_add_i32 s55, s55, 0x80080
	buffer_load_dwordx4 v156, s[8:11], s58 offen lds
	s_mov_b32 m0, s35
	s_nop 0
	buffer_load_dwordx4 v153, s[8:11], s55 offen lds
	s_mov_b32 m0, s36
	s_nop 0
	buffer_load_dwordx4 v156, s[8:11], s55 offen lds
	s_mov_b32 m0, s31
	s_nop 0
	buffer_load_dwordx4 v151, s[48:51], s56 offen lds
	s_mov_b32 m0, s34
	s_nop 0
	buffer_load_dwordx4 v155, s[48:51], s56 offen lds
	s_waitcnt vmcnt(8)
	s_waitcnt lgkmcnt(0)
	s_barrier
	s_setprio 1
	s_waitcnt lgkmcnt(0)
	v_mfma_f32_16x16x32_f16 v[54:57], v[164:167], v[196:199], v[54:57]
	v_mfma_f32_16x16x32_f16 v[66:69], v[168:171], v[196:199], v[66:69]
	v_mfma_f32_16x16x32_f16 v[30:33], v[164:167], v[204:207], v[30:33]
	v_mfma_f32_16x16x32_f16 v[38:41], v[168:171], v[204:207], v[38:41]
	v_mfma_f32_16x16x32_f16 v[10:13], v[164:167], v[216:219], v[10:13]
	v_mfma_f32_16x16x32_f16 v[18:21], v[168:171], v[216:219], v[18:21]
	v_mfma_f32_16x16x32_f16 v[2:5], v[164:167], v[220:223], v[2:5]
	v_mfma_f32_16x16x32_f16 v[6:9], v[168:171], v[220:223], v[6:9]
	v_mfma_f32_16x16x32_f16 v[54:57], v[172:175], v[208:211], v[54:57]
	v_mfma_f32_16x16x32_f16 v[66:69], v[176:179], v[208:211], v[66:69]
	v_mfma_f32_16x16x32_f16 v[30:33], v[172:175], v[212:215], v[30:33]
	v_mfma_f32_16x16x32_f16 v[38:41], v[176:179], v[212:215], v[38:41]
	v_mfma_f32_16x16x32_f16 v[10:13], v[172:175], v[224:227], v[10:13]
	v_mfma_f32_16x16x32_f16 v[18:21], v[176:179], v[224:227], v[18:21]
	v_mfma_f32_16x16x32_f16 v[2:5], v[172:175], v[228:231], v[2:5]
	v_mfma_f32_16x16x32_f16 v[6:9], v[176:179], v[228:231], v[6:9]
	s_setprio 0
	s_setprio 1
	v_mfma_f32_16x16x32_f16 v[106:109], v[180:183], v[196:199], v[106:109]
	v_mfma_f32_16x16x32_f16 v[114:117], v[184:187], v[196:199], v[114:117]
	v_mfma_f32_16x16x32_f16 v[82:85], v[180:183], v[204:207], v[82:85]
	v_mfma_f32_16x16x32_f16 v[90:93], v[184:187], v[204:207], v[90:93]
	v_mfma_f32_16x16x32_f16 v[46:49], v[180:183], v[216:219], v[46:49]
	v_mfma_f32_16x16x32_f16 v[58:61], v[184:187], v[216:219], v[58:61]
	v_mfma_f32_16x16x32_f16 v[26:29], v[180:183], v[220:223], v[26:29]
	v_mfma_f32_16x16x32_f16 v[50:53], v[184:187], v[220:223], v[50:53]
	v_mfma_f32_16x16x32_f16 v[106:109], v[188:191], v[208:211], v[106:109]
	v_mfma_f32_16x16x32_f16 v[114:117], v[192:195], v[208:211], v[114:117]
	v_mfma_f32_16x16x32_f16 v[82:85], v[188:191], v[212:215], v[82:85]
	v_mfma_f32_16x16x32_f16 v[90:93], v[192:195], v[212:215], v[90:93]
	v_mfma_f32_16x16x32_f16 v[46:49], v[188:191], v[224:227], v[46:49]
	v_mfma_f32_16x16x32_f16 v[58:61], v[192:195], v[224:227], v[58:61]
	v_mfma_f32_16x16x32_f16 v[26:29], v[188:191], v[228:231], v[26:29]
	v_mfma_f32_16x16x32_f16 v[50:53], v[192:195], v[228:231], v[50:53]
	s_setprio 0
	s_barrier

.Lc0r_final:
	s_add_i32 s81, s64, 0x80
	s_and_b64 s[10:11], s[10:11], exec
	s_cselect_b32 s84, s24, s81
	s_cselect_b32 s85, s25, s65
	s_add_i32 s10, 0, 0x10000
	v_add_u32_e32 v3, s10, v208
	v_add_u32_e32 v144, s10, v209
	s_add_i32 s10, 0, 0x14000
	ds_read_b128 v[116:119], v3
	ds_read_b128 v[120:123], v3 offset:2048
	ds_read_b128 v[140:143], v144
	ds_read_b128 v[144:147], v144 offset:2048
	v_add_u32_e32 v3, s10, v208
	v_add_u32_e32 v176, s10, v209
	ds_read_b128 v[164:167], v3
	ds_read_b128 v[168:171], v3 offset:2048
	ds_read_b128 v[172:175], v176
	ds_read_b128 v[176:179], v176 offset:2048
	s_add_i32 s81, s84, 0x80
	s_add_i32 s82, s85, 0x80
	s_add_i32 s10, s29, s64
	s_mov_b32 m0, s53
	ds_read_b128 v[180:183], v214
	ds_read_b128 v[184:187], v214 offset:2048
	ds_read_b128 v[188:191], v215
	ds_read_b128 v[192:195], v215 offset:2048
	ds_read_b128 v[196:199], v214 offset:4096
	ds_read_b128 v[216:219], v214 offset:6144
	ds_read_b128 v[220:223], v215 offset:4096
	ds_read_b128 v[224:227], v215 offset:6144
	buffer_load_dwordx4 v204, s[48:51], s10 offen lds
	s_mov_b32 m0, s54
	s_nop 0
	buffer_load_dwordx4 v206, s[48:51], s10 offen lds
	s_waitcnt vmcnt(8)
	s_waitcnt lgkmcnt(0)
	s_barrier
	s_setprio 1
	s_waitcnt lgkmcnt(0)
	v_mfma_f32_16x16x32_bf16 v[160:163], v[116:119], v[180:183], v[160:163]
	v_mfma_f32_16x16x32_bf16 v[152:155], v[120:123], v[180:183], v[152:155]
	v_mfma_f32_16x16x32_bf16 v[132:135], v[116:119], v[184:187], v[132:135]
	v_mfma_f32_16x16x32_bf16 v[124:127], v[120:123], v[184:187], v[124:127]
	v_mfma_f32_16x16x32_bf16 v[108:111], v[116:119], v[196:199], v[108:111]
	v_mfma_f32_16x16x32_bf16 v[100:103], v[120:123], v[196:199], v[100:103]
	v_mfma_f32_16x16x32_bf16 v[92:95], v[116:119], v[216:219], v[92:95]
	v_mfma_f32_16x16x32_bf16 v[84:87], v[120:123], v[216:219], v[84:87]
	v_mfma_f32_16x16x32_bf16 v[160:163], v[140:143], v[188:191], v[160:163]
	v_mfma_f32_16x16x32_bf16 v[152:155], v[144:147], v[188:191], v[152:155]
	v_mfma_f32_16x16x32_bf16 v[132:135], v[140:143], v[192:195], v[132:135]
	v_mfma_f32_16x16x32_bf16 v[124:127], v[144:147], v[192:195], v[124:127]
	v_mfma_f32_16x16x32_bf16 v[108:111], v[140:143], v[220:223], v[108:111]
	v_mfma_f32_16x16x32_bf16 v[100:103], v[144:147], v[220:223], v[100:103]
	v_mfma_f32_16x16x32_bf16 v[92:95], v[140:143], v[224:227], v[92:95]
	v_mfma_f32_16x16x32_bf16 v[84:87], v[144:147], v[224:227], v[84:87]
	s_setprio 0
	s_setprio 1
	v_mfma_f32_16x16x32_bf16 v[156:159], v[164:167], v[180:183], v[156:159]
	v_mfma_f32_16x16x32_bf16 v[148:151], v[168:171], v[180:183], v[148:151]
	v_mfma_f32_16x16x32_bf16 v[136:139], v[164:167], v[184:187], v[136:139]
	v_mfma_f32_16x16x32_bf16 v[128:131], v[168:171], v[184:187], v[128:131]
	v_mfma_f32_16x16x32_bf16 v[112:115], v[164:167], v[196:199], v[112:115]
	v_mfma_f32_16x16x32_bf16 v[104:107], v[168:171], v[196:199], v[104:107]
	v_mfma_f32_16x16x32_bf16 v[96:99], v[164:167], v[216:219], v[96:99]
	v_mfma_f32_16x16x32_bf16 v[88:91], v[168:171], v[216:219], v[88:91]
	v_mfma_f32_16x16x32_bf16 v[156:159], v[172:175], v[188:191], v[156:159]
	v_mfma_f32_16x16x32_bf16 v[148:151], v[176:179], v[188:191], v[148:151]
	v_mfma_f32_16x16x32_bf16 v[136:139], v[172:175], v[192:195], v[136:139]
	v_mfma_f32_16x16x32_bf16 v[128:131], v[176:179], v[192:195], v[128:131]
	v_mfma_f32_16x16x32_bf16 v[112:115], v[172:175], v[220:223], v[112:115]
	v_mfma_f32_16x16x32_bf16 v[104:107], v[176:179], v[220:223], v[104:107]
	v_mfma_f32_16x16x32_bf16 v[96:99], v[172:175], v[224:227], v[96:99]
	v_mfma_f32_16x16x32_bf16 v[88:91], v[176:179], v[224:227], v[88:91]
	s_setprio 0
	s_barrier
	s_mov_b32 s10, s50
	s_mov_b32 s11, s51
	ds_read_b128 v[180:183], v214 offset:16384
	ds_read_b128 v[184:187], v214 offset:18432
	ds_read_b128 v[188:191], v215 offset:16384
	ds_read_b128 v[192:195], v215 offset:18432
	ds_read_b128 v[196:199], v214 offset:20480
	ds_read_b128 v[216:219], v214 offset:22528
	ds_read_b128 v[220:223], v215 offset:20480
	ds_read_b128 v[224:227], v215 offset:22528
	s_add_i32 s85, s85, s29
	s_waitcnt vmcnt(2)
	s_waitcnt lgkmcnt(0)
	s_barrier
	s_setprio 1
	s_waitcnt lgkmcnt(0)
	v_mfma_f32_16x16x32_bf16 v[76:79], v[116:119], v[180:183], v[76:79]
	v_mfma_f32_16x16x32_bf16 v[68:71], v[120:123], v[180:183], v[68:71]
	v_mfma_f32_16x16x32_bf16 v[60:63], v[116:119], v[184:187], v[60:63]
	v_mfma_f32_16x16x32_bf16 v[52:55], v[120:123], v[184:187], v[52:55]
	v_mfma_f32_16x16x32_bf16 v[44:47], v[116:119], v[196:199], v[44:47]
	v_mfma_f32_16x16x32_bf16 v[36:39], v[120:123], v[196:199], v[36:39]
	v_mfma_f32_16x16x32_bf16 v[24:27], v[116:119], v[216:219], v[24:27]
	v_mfma_f32_16x16x32_bf16 v[20:23], v[120:123], v[216:219], v[20:23]
	v_mfma_f32_16x16x32_bf16 v[76:79], v[140:143], v[188:191], v[76:79]
	v_mfma_f32_16x16x32_bf16 v[68:71], v[144:147], v[188:191], v[68:71]
	v_mfma_f32_16x16x32_bf16 v[60:63], v[140:143], v[192:195], v[60:63]
	v_mfma_f32_16x16x32_bf16 v[52:55], v[144:147], v[192:195], v[52:55]
	v_mfma_f32_16x16x32_bf16 v[44:47], v[140:143], v[220:223], v[44:47]
	v_mfma_f32_16x16x32_bf16 v[36:39], v[144:147], v[220:223], v[36:39]
	v_mfma_f32_16x16x32_bf16 v[24:27], v[140:143], v[224:227], v[24:27]
	v_mfma_f32_16x16x32_bf16 v[20:23], v[144:147], v[224:227], v[20:23]
	s_setprio 0
	s_setprio 1
	v_mfma_f32_16x16x32_bf16 v[80:83], v[164:167], v[180:183], v[80:83]
	v_mfma_f32_16x16x32_bf16 v[72:75], v[168:171], v[180:183], v[72:75]
	v_mfma_f32_16x16x32_bf16 v[64:67], v[164:167], v[184:187], v[64:67]
	v_mfma_f32_16x16x32_bf16 v[56:59], v[168:171], v[184:187], v[56:59]
	v_mfma_f32_16x16x32_bf16 v[48:51], v[164:167], v[196:199], v[48:51]
	v_mfma_f32_16x16x32_bf16 v[40:43], v[168:171], v[196:199], v[40:43]
	v_mfma_f32_16x16x32_bf16 v[28:31], v[164:167], v[216:219], v[28:31]
	v_mfma_f32_16x16x32_bf16 v[32:35], v[168:171], v[216:219], v[32:35]
	v_mfma_f32_16x16x32_bf16 v[80:83], v[172:175], v[188:191], v[80:83]
	v_mfma_f32_16x16x32_bf16 v[72:75], v[176:179], v[188:191], v[72:75]
	v_mfma_f32_16x16x32_bf16 v[64:67], v[172:175], v[192:195], v[64:67]
	v_mfma_f32_16x16x32_bf16 v[56:59], v[176:179], v[192:195], v[56:59]
	v_mfma_f32_16x16x32_bf16 v[48:51], v[172:175], v[220:223], v[48:51]
	v_mfma_f32_16x16x32_bf16 v[40:43], v[176:179], v[220:223], v[40:43]
	v_mfma_f32_16x16x32_bf16 v[28:31], v[172:175], v[224:227], v[28:31]
	v_mfma_f32_16x16x32_bf16 v[32:35], v[176:179], v[224:227], v[32:35]
	s_setprio 0
	s_barrier
	s_add_i32 s85, 0, 0x18000
	v_add_u32_e32 v3, s85, v208
	v_add_u32_e32 v144, s85, v209
	s_add_i32 s85, 0, 0x1c000
	ds_read_b128 v[116:119], v3
	ds_read_b128 v[120:123], v3 offset:2048
	ds_read_b128 v[140:143], v144
	ds_read_b128 v[144:147], v144 offset:2048
	v_add_u32_e32 v3, s85, v208
	v_add_u32_e32 v176, s85, v209
	ds_read_b128 v[164:167], v3
	ds_read_b128 v[168:171], v3 offset:2048
	ds_read_b128 v[172:175], v176
	ds_read_b128 v[176:179], v176 offset:2048
	s_add_i32 s84, s84, s29
	ds_read_b128 v[180:183], v214 offset:32768
	ds_read_b128 v[184:187], v214 offset:34816
	ds_read_b128 v[188:191], v215 offset:32768
	ds_read_b128 v[192:195], v215 offset:34816
	ds_read_b128 v[196:199], v214 offset:36864
	ds_read_b128 v[216:219], v214 offset:38912
	ds_read_b128 v[220:223], v215 offset:36864
	ds_read_b128 v[224:227], v215 offset:38912
	s_waitcnt vmcnt(0)
	s_waitcnt lgkmcnt(0)
	s_barrier
	s_setprio 1
	s_waitcnt lgkmcnt(0)
	v_mfma_f32_16x16x32_bf16 v[160:163], v[116:119], v[180:183], v[160:163]
	v_mfma_f32_16x16x32_bf16 v[152:155], v[120:123], v[180:183], v[152:155]
	v_mfma_f32_16x16x32_bf16 v[132:135], v[116:119], v[184:187], v[132:135]
	v_mfma_f32_16x16x32_bf16 v[124:127], v[120:123], v[184:187], v[124:127]
	v_mfma_f32_16x16x32_bf16 v[108:111], v[116:119], v[196:199], v[108:111]
	v_mfma_f32_16x16x32_bf16 v[100:103], v[120:123], v[196:199], v[100:103]
	v_mfma_f32_16x16x32_bf16 v[92:95], v[116:119], v[216:219], v[92:95]
	v_mfma_f32_16x16x32_bf16 v[84:87], v[120:123], v[216:219], v[84:87]
	v_mfma_f32_16x16x32_bf16 v[160:163], v[140:143], v[188:191], v[160:163]
	v_mfma_f32_16x16x32_bf16 v[152:155], v[144:147], v[188:191], v[152:155]
	v_mfma_f32_16x16x32_bf16 v[132:135], v[140:143], v[192:195], v[132:135]
	v_mfma_f32_16x16x32_bf16 v[124:127], v[144:147], v[192:195], v[124:127]
	v_mfma_f32_16x16x32_bf16 v[108:111], v[140:143], v[220:223], v[108:111]
	v_mfma_f32_16x16x32_bf16 v[100:103], v[144:147], v[220:223], v[100:103]
	v_mfma_f32_16x16x32_bf16 v[92:95], v[140:143], v[224:227], v[92:95]
	v_mfma_f32_16x16x32_bf16 v[84:87], v[144:147], v[224:227], v[84:87]
	s_setprio 0
	s_setprio 1
	v_mfma_f32_16x16x32_bf16 v[156:159], v[164:167], v[180:183], v[156:159]
	v_mfma_f32_16x16x32_bf16 v[148:151], v[168:171], v[180:183], v[148:151]
	v_mfma_f32_16x16x32_bf16 v[136:139], v[164:167], v[184:187], v[136:139]
	v_mfma_f32_16x16x32_bf16 v[128:131], v[168:171], v[184:187], v[128:131]
	v_mfma_f32_16x16x32_bf16 v[112:115], v[164:167], v[196:199], v[112:115]
	v_mfma_f32_16x16x32_bf16 v[104:107], v[168:171], v[196:199], v[104:107]
	v_mfma_f32_16x16x32_bf16 v[96:99], v[164:167], v[216:219], v[96:99]
	v_mfma_f32_16x16x32_bf16 v[88:91], v[168:171], v[216:219], v[88:91]
	v_mfma_f32_16x16x32_bf16 v[156:159], v[172:175], v[188:191], v[156:159]
	v_mfma_f32_16x16x32_bf16 v[148:151], v[176:179], v[188:191], v[148:151]
	v_mfma_f32_16x16x32_bf16 v[136:139], v[172:175], v[192:195], v[136:139]
	v_mfma_f32_16x16x32_bf16 v[128:131], v[176:179], v[192:195], v[128:131]
	v_mfma_f32_16x16x32_bf16 v[112:115], v[172:175], v[220:223], v[112:115]
	v_mfma_f32_16x16x32_bf16 v[104:107], v[176:179], v[220:223], v[104:107]
	v_mfma_f32_16x16x32_bf16 v[96:99], v[172:175], v[224:227], v[96:99]
	v_mfma_f32_16x16x32_bf16 v[88:91], v[176:179], v[224:227], v[88:91]
	s_setprio 0
	s_barrier
	ds_read_b128 v[180:183], v214 offset:49152
	ds_read_b128 v[184:187], v214 offset:51200
	ds_read_b128 v[188:191], v215 offset:49152
	ds_read_b128 v[192:195], v215 offset:51200
	ds_read_b128 v[196:199], v214 offset:53248
	ds_read_b128 v[216:219], v214 offset:55296
	ds_read_b128 v[220:223], v215 offset:53248
	ds_read_b128 v[224:227], v215 offset:55296
	s_add_i32 s82, s82, s29
	s_waitcnt vmcnt(0)
	s_waitcnt lgkmcnt(0)
	s_barrier
	s_setprio 1
	s_waitcnt lgkmcnt(0)
	v_mfma_f32_16x16x32_bf16 v[76:79], v[116:119], v[180:183], v[76:79]
	v_mfma_f32_16x16x32_bf16 v[68:71], v[120:123], v[180:183], v[68:71]
	v_mfma_f32_16x16x32_bf16 v[60:63], v[116:119], v[184:187], v[60:63]
	v_mfma_f32_16x16x32_bf16 v[52:55], v[120:123], v[184:187], v[52:55]
	v_mfma_f32_16x16x32_bf16 v[44:47], v[116:119], v[196:199], v[44:47]
	v_mfma_f32_16x16x32_bf16 v[36:39], v[120:123], v[196:199], v[36:39]
	v_mfma_f32_16x16x32_bf16 v[24:27], v[116:119], v[216:219], v[24:27]
	v_mfma_f32_16x16x32_bf16 v[20:23], v[120:123], v[216:219], v[20:23]
	v_mfma_f32_16x16x32_bf16 v[76:79], v[140:143], v[188:191], v[76:79]
	v_mfma_f32_16x16x32_bf16 v[68:71], v[144:147], v[188:191], v[68:71]
	v_mfma_f32_16x16x32_bf16 v[60:63], v[140:143], v[192:195], v[60:63]
	v_mfma_f32_16x16x32_bf16 v[52:55], v[144:147], v[192:195], v[52:55]
	v_mfma_f32_16x16x32_bf16 v[44:47], v[140:143], v[220:223], v[44:47]
	v_mfma_f32_16x16x32_bf16 v[36:39], v[144:147], v[220:223], v[36:39]
	v_mfma_f32_16x16x32_bf16 v[24:27], v[140:143], v[224:227], v[24:27]
	v_mfma_f32_16x16x32_bf16 v[20:23], v[144:147], v[224:227], v[20:23]
	s_setprio 0
	s_setprio 1
	v_mfma_f32_16x16x32_bf16 v[80:83], v[164:167], v[180:183], v[80:83]
	v_mfma_f32_16x16x32_bf16 v[72:75], v[168:171], v[180:183], v[72:75]
	v_mfma_f32_16x16x32_bf16 v[64:67], v[164:167], v[184:187], v[64:67]
	v_mfma_f32_16x16x32_bf16 v[56:59], v[168:171], v[184:187], v[56:59]
	v_mfma_f32_16x16x32_bf16 v[48:51], v[164:167], v[196:199], v[48:51]
	v_mfma_f32_16x16x32_bf16 v[40:43], v[168:171], v[196:199], v[40:43]
	v_mfma_f32_16x16x32_bf16 v[28:31], v[164:167], v[216:219], v[28:31]
	v_mfma_f32_16x16x32_bf16 v[32:35], v[168:171], v[216:219], v[32:35]
	v_mfma_f32_16x16x32_bf16 v[80:83], v[172:175], v[188:191], v[80:83]
	v_mfma_f32_16x16x32_bf16 v[72:75], v[176:179], v[188:191], v[72:75]
	v_mfma_f32_16x16x32_bf16 v[64:67], v[172:175], v[192:195], v[64:67]
	v_mfma_f32_16x16x32_bf16 v[56:59], v[176:179], v[192:195], v[56:59]
	v_mfma_f32_16x16x32_bf16 v[48:51], v[172:175], v[220:223], v[48:51]
	v_mfma_f32_16x16x32_bf16 v[40:43], v[176:179], v[220:223], v[40:43]
	v_mfma_f32_16x16x32_bf16 v[28:31], v[172:175], v[224:227], v[28:31]
	v_mfma_f32_16x16x32_bf16 v[32:35], v[176:179], v[224:227], v[32:35]
	s_setprio 0
	s_barrier
	s_branch .Lc0r_tail
.LBB0_382:
	s_cmp_eq_u32 s78, 0
	s_cbranch_scc1 .Lc0r_first
	s_cmp_eq_u32 s78, s52
	s_cbranch_scc0 .Lc0r_norm
	s_cmp_eq_u64 s[4:5], 0
	s_cbranch_scc1 .Lc0r_final
.Lc0r_norm:
	s_add_i32 s81, s64, 0x80
	s_and_b64 s[10:11], s[10:11], exec
	s_cselect_b32 s84, s24, s81
	s_cselect_b32 s85, s25, s65
	s_add_i32 s10, 0, 0x10000
	v_add_u32_e32 v3, s10, v208
	v_add_u32_e32 v144, s10, v209
	s_add_i32 s10, 0, 0x14000
	ds_read_b128 v[116:119], v3
	ds_read_b128 v[120:123], v3 offset:2048
	ds_read_b128 v[140:143], v144
	ds_read_b128 v[144:147], v144 offset:2048
	v_add_u32_e32 v3, s10, v208
	v_add_u32_e32 v176, s10, v209
	ds_read_b128 v[164:167], v3
	ds_read_b128 v[168:171], v3 offset:2048
	ds_read_b128 v[172:175], v176
	ds_read_b128 v[176:179], v176 offset:2048
	s_add_i32 s81, s84, 0x80
	s_add_i32 s82, s85, 0x80
	s_add_i32 s10, s29, s64
	s_mov_b32 m0, s53
	ds_read_b128 v[180:183], v214
	ds_read_b128 v[184:187], v214 offset:2048
	ds_read_b128 v[188:191], v215
	ds_read_b128 v[192:195], v215 offset:2048
	ds_read_b128 v[196:199], v214 offset:4096
	ds_read_b128 v[216:219], v214 offset:6144
	ds_read_b128 v[220:223], v215 offset:4096
	ds_read_b128 v[224:227], v215 offset:6144
	buffer_load_dwordx4 v204, s[48:51], s10 offen lds
	s_mov_b32 m0, s54
	s_nop 0
	buffer_load_dwordx4 v206, s[48:51], s10 offen lds
	s_waitcnt vmcnt(8)
	s_waitcnt lgkmcnt(0)
	s_barrier
	s_setprio 1
	s_waitcnt lgkmcnt(0)
	v_mfma_f32_16x16x32_bf16 v[160:163], v[116:119], v[180:183], v[160:163]
	v_mfma_f32_16x16x32_bf16 v[152:155], v[120:123], v[180:183], v[152:155]
	v_mfma_f32_16x16x32_bf16 v[132:135], v[116:119], v[184:187], v[132:135]
	v_mfma_f32_16x16x32_bf16 v[124:127], v[120:123], v[184:187], v[124:127]
	v_mfma_f32_16x16x32_bf16 v[108:111], v[116:119], v[196:199], v[108:111]
	v_mfma_f32_16x16x32_bf16 v[100:103], v[120:123], v[196:199], v[100:103]
	v_mfma_f32_16x16x32_bf16 v[92:95], v[116:119], v[216:219], v[92:95]
	v_mfma_f32_16x16x32_bf16 v[84:87], v[120:123], v[216:219], v[84:87]
	v_mfma_f32_16x16x32_bf16 v[160:163], v[140:143], v[188:191], v[160:163]
	v_mfma_f32_16x16x32_bf16 v[152:155], v[144:147], v[188:191], v[152:155]
	v_mfma_f32_16x16x32_bf16 v[132:135], v[140:143], v[192:195], v[132:135]
	v_mfma_f32_16x16x32_bf16 v[124:127], v[144:147], v[192:195], v[124:127]
	v_mfma_f32_16x16x32_bf16 v[108:111], v[140:143], v[220:223], v[108:111]
	v_mfma_f32_16x16x32_bf16 v[100:103], v[144:147], v[220:223], v[100:103]
	v_mfma_f32_16x16x32_bf16 v[92:95], v[140:143], v[224:227], v[92:95]
	v_mfma_f32_16x16x32_bf16 v[84:87], v[144:147], v[224:227], v[84:87]
	s_setprio 0
	s_setprio 1
	v_mfma_f32_16x16x32_bf16 v[156:159], v[164:167], v[180:183], v[156:159]
	v_mfma_f32_16x16x32_bf16 v[148:151], v[168:171], v[180:183], v[148:151]
	v_mfma_f32_16x16x32_bf16 v[136:139], v[164:167], v[184:187], v[136:139]
	v_mfma_f32_16x16x32_bf16 v[128:131], v[168:171], v[184:187], v[128:131]
	v_mfma_f32_16x16x32_bf16 v[112:115], v[164:167], v[196:199], v[112:115]
	v_mfma_f32_16x16x32_bf16 v[104:107], v[168:171], v[196:199], v[104:107]
	v_mfma_f32_16x16x32_bf16 v[96:99], v[164:167], v[216:219], v[96:99]
	v_mfma_f32_16x16x32_bf16 v[88:91], v[168:171], v[216:219], v[88:91]
	v_mfma_f32_16x16x32_bf16 v[156:159], v[172:175], v[188:191], v[156:159]
	v_mfma_f32_16x16x32_bf16 v[148:151], v[176:179], v[188:191], v[148:151]
	v_mfma_f32_16x16x32_bf16 v[136:139], v[172:175], v[192:195], v[136:139]
	v_mfma_f32_16x16x32_bf16 v[128:131], v[176:179], v[192:195], v[128:131]
	v_mfma_f32_16x16x32_bf16 v[112:115], v[172:175], v[220:223], v[112:115]
	v_mfma_f32_16x16x32_bf16 v[104:107], v[176:179], v[220:223], v[104:107]
	v_mfma_f32_16x16x32_bf16 v[96:99], v[172:175], v[224:227], v[96:99]
	v_mfma_f32_16x16x32_bf16 v[88:91], v[176:179], v[224:227], v[88:91]
	s_setprio 0
	s_barrier
	s_mov_b32 m0, s34
	s_mov_b32 s10, s50
	s_mov_b32 s11, s51
	ds_read_b128 v[180:183], v214 offset:16384
	ds_read_b128 v[184:187], v214 offset:18432
	ds_read_b128 v[188:191], v215 offset:16384
	ds_read_b128 v[192:195], v215 offset:18432
	ds_read_b128 v[196:199], v214 offset:20480
	ds_read_b128 v[216:219], v214 offset:22528
	ds_read_b128 v[220:223], v215 offset:20480
	ds_read_b128 v[224:227], v215 offset:22528
	buffer_load_dwordx4 v205, s[8:11], s85 offen lds
	s_mov_b32 m0, s35
	s_nop 0
	buffer_load_dwordx4 v207, s[8:11], s85 offen lds
	s_add_i32 s85, s85, s29
	s_mov_b32 m0, s36
	s_nop 0
	buffer_load_dwordx4 v205, s[8:11], s85 offen lds
	s_mov_b32 m0, s37
	s_nop 0
	buffer_load_dwordx4 v207, s[8:11], s85 offen lds
	s_mov_b32 m0, s31
	s_nop 0
	buffer_load_dwordx4 v204, s[48:51], s84 offen lds
	s_mov_b32 m0, s38
	s_nop 0
	buffer_load_dwordx4 v206, s[48:51], s84 offen lds
	s_waitcnt vmcnt(8)
	s_waitcnt lgkmcnt(0)
	s_barrier
	s_setprio 1
	s_waitcnt lgkmcnt(0)
	v_mfma_f32_16x16x32_bf16 v[76:79], v[116:119], v[180:183], v[76:79]
	v_mfma_f32_16x16x32_bf16 v[68:71], v[120:123], v[180:183], v[68:71]
	v_mfma_f32_16x16x32_bf16 v[60:63], v[116:119], v[184:187], v[60:63]
	v_mfma_f32_16x16x32_bf16 v[52:55], v[120:123], v[184:187], v[52:55]
	v_mfma_f32_16x16x32_bf16 v[44:47], v[116:119], v[196:199], v[44:47]
	v_mfma_f32_16x16x32_bf16 v[36:39], v[120:123], v[196:199], v[36:39]
	v_mfma_f32_16x16x32_bf16 v[24:27], v[116:119], v[216:219], v[24:27]
	v_mfma_f32_16x16x32_bf16 v[20:23], v[120:123], v[216:219], v[20:23]
	v_mfma_f32_16x16x32_bf16 v[76:79], v[140:143], v[188:191], v[76:79]
	v_mfma_f32_16x16x32_bf16 v[68:71], v[144:147], v[188:191], v[68:71]
	v_mfma_f32_16x16x32_bf16 v[60:63], v[140:143], v[192:195], v[60:63]
	v_mfma_f32_16x16x32_bf16 v[52:55], v[144:147], v[192:195], v[52:55]
	v_mfma_f32_16x16x32_bf16 v[44:47], v[140:143], v[220:223], v[44:47]
	v_mfma_f32_16x16x32_bf16 v[36:39], v[144:147], v[220:223], v[36:39]
	v_mfma_f32_16x16x32_bf16 v[24:27], v[140:143], v[224:227], v[24:27]
	v_mfma_f32_16x16x32_bf16 v[20:23], v[144:147], v[224:227], v[20:23]
	s_setprio 0
	s_setprio 1
	v_mfma_f32_16x16x32_bf16 v[80:83], v[164:167], v[180:183], v[80:83]
	v_mfma_f32_16x16x32_bf16 v[72:75], v[168:171], v[180:183], v[72:75]
	v_mfma_f32_16x16x32_bf16 v[64:67], v[164:167], v[184:187], v[64:67]
	v_mfma_f32_16x16x32_bf16 v[56:59], v[168:171], v[184:187], v[56:59]
	v_mfma_f32_16x16x32_bf16 v[48:51], v[164:167], v[196:199], v[48:51]
	v_mfma_f32_16x16x32_bf16 v[40:43], v[168:171], v[196:199], v[40:43]
	v_mfma_f32_16x16x32_bf16 v[28:31], v[164:167], v[216:219], v[28:31]
	v_mfma_f32_16x16x32_bf16 v[32:35], v[168:171], v[216:219], v[32:35]
	v_mfma_f32_16x16x32_bf16 v[80:83], v[172:175], v[188:191], v[80:83]
	v_mfma_f32_16x16x32_bf16 v[72:75], v[176:179], v[188:191], v[72:75]
	v_mfma_f32_16x16x32_bf16 v[64:67], v[172:175], v[192:195], v[64:67]
	v_mfma_f32_16x16x32_bf16 v[56:59], v[176:179], v[192:195], v[56:59]
	v_mfma_f32_16x16x32_bf16 v[48:51], v[172:175], v[220:223], v[48:51]
	v_mfma_f32_16x16x32_bf16 v[40:43], v[176:179], v[220:223], v[40:43]
	v_mfma_f32_16x16x32_bf16 v[28:31], v[172:175], v[224:227], v[28:31]
	v_mfma_f32_16x16x32_bf16 v[32:35], v[176:179], v[224:227], v[32:35]
	s_setprio 0
	s_barrier
	s_add_i32 s85, 0, 0x18000
	v_add_u32_e32 v3, s85, v208
	v_add_u32_e32 v144, s85, v209
	s_add_i32 s85, 0, 0x1c000
	ds_read_b128 v[116:119], v3
	ds_read_b128 v[120:123], v3 offset:2048
	ds_read_b128 v[140:143], v144
	ds_read_b128 v[144:147], v144 offset:2048
	v_add_u32_e32 v3, s85, v208
	v_add_u32_e32 v176, s85, v209
	ds_read_b128 v[164:167], v3
	ds_read_b128 v[168:171], v3 offset:2048
	ds_read_b128 v[172:175], v176
	ds_read_b128 v[176:179], v176 offset:2048
	s_add_i32 s84, s84, s29
	s_mov_b32 m0, s39
	ds_read_b128 v[180:183], v214 offset:32768
	ds_read_b128 v[184:187], v214 offset:34816
	ds_read_b128 v[188:191], v215 offset:32768
	ds_read_b128 v[192:195], v215 offset:34816
	ds_read_b128 v[196:199], v214 offset:36864
	ds_read_b128 v[216:219], v214 offset:38912
	ds_read_b128 v[220:223], v215 offset:36864
	ds_read_b128 v[224:227], v215 offset:38912
	buffer_load_dwordx4 v204, s[48:51], s84 offen lds
	s_mov_b32 m0, s40
	s_nop 0
	buffer_load_dwordx4 v206, s[48:51], s84 offen lds
	s_waitcnt vmcnt(8)
	s_waitcnt lgkmcnt(0)
	s_barrier
	s_setprio 1
	s_waitcnt lgkmcnt(0)
	v_mfma_f32_16x16x32_bf16 v[160:163], v[116:119], v[180:183], v[160:163]
	v_mfma_f32_16x16x32_bf16 v[152:155], v[120:123], v[180:183], v[152:155]
	v_mfma_f32_16x16x32_bf16 v[132:135], v[116:119], v[184:187], v[132:135]
	v_mfma_f32_16x16x32_bf16 v[124:127], v[120:123], v[184:187], v[124:127]
	v_mfma_f32_16x16x32_bf16 v[108:111], v[116:119], v[196:199], v[108:111]
	v_mfma_f32_16x16x32_bf16 v[100:103], v[120:123], v[196:199], v[100:103]
	v_mfma_f32_16x16x32_bf16 v[92:95], v[116:119], v[216:219], v[92:95]
	v_mfma_f32_16x16x32_bf16 v[84:87], v[120:123], v[216:219], v[84:87]
	v_mfma_f32_16x16x32_bf16 v[160:163], v[140:143], v[188:191], v[160:163]
	v_mfma_f32_16x16x32_bf16 v[152:155], v[144:147], v[188:191], v[152:155]
	v_mfma_f32_16x16x32_bf16 v[132:135], v[140:143], v[192:195], v[132:135]
	v_mfma_f32_16x16x32_bf16 v[124:127], v[144:147], v[192:195], v[124:127]
	v_mfma_f32_16x16x32_bf16 v[108:111], v[140:143], v[220:223], v[108:111]
	v_mfma_f32_16x16x32_bf16 v[100:103], v[144:147], v[220:223], v[100:103]
	v_mfma_f32_16x16x32_bf16 v[92:95], v[140:143], v[224:227], v[92:95]
	v_mfma_f32_16x16x32_bf16 v[84:87], v[144:147], v[224:227], v[84:87]
	s_setprio 0
	s_setprio 1
	v_mfma_f32_16x16x32_bf16 v[156:159], v[164:167], v[180:183], v[156:159]
	v_mfma_f32_16x16x32_bf16 v[148:151], v[168:171], v[180:183], v[148:151]
	v_mfma_f32_16x16x32_bf16 v[136:139], v[164:167], v[184:187], v[136:139]
	v_mfma_f32_16x16x32_bf16 v[128:131], v[168:171], v[184:187], v[128:131]
	v_mfma_f32_16x16x32_bf16 v[112:115], v[164:167], v[196:199], v[112:115]
	v_mfma_f32_16x16x32_bf16 v[104:107], v[168:171], v[196:199], v[104:107]
	v_mfma_f32_16x16x32_bf16 v[96:99], v[164:167], v[216:219], v[96:99]
	v_mfma_f32_16x16x32_bf16 v[88:91], v[168:171], v[216:219], v[88:91]
	v_mfma_f32_16x16x32_bf16 v[156:159], v[172:175], v[188:191], v[156:159]
	v_mfma_f32_16x16x32_bf16 v[148:151], v[176:179], v[188:191], v[148:151]
	v_mfma_f32_16x16x32_bf16 v[136:139], v[172:175], v[192:195], v[136:139]
	v_mfma_f32_16x16x32_bf16 v[128:131], v[176:179], v[192:195], v[128:131]
	v_mfma_f32_16x16x32_bf16 v[112:115], v[172:175], v[220:223], v[112:115]
	v_mfma_f32_16x16x32_bf16 v[104:107], v[176:179], v[220:223], v[104:107]
	v_mfma_f32_16x16x32_bf16 v[96:99], v[172:175], v[224:227], v[96:99]
	v_mfma_f32_16x16x32_bf16 v[88:91], v[176:179], v[224:227], v[88:91]
	s_setprio 0
	s_barrier
	s_mov_b32 m0, s41
	ds_read_b128 v[180:183], v214 offset:49152
	ds_read_b128 v[184:187], v214 offset:51200
	ds_read_b128 v[188:191], v215 offset:49152
	ds_read_b128 v[192:195], v215 offset:51200
	ds_read_b128 v[196:199], v214 offset:53248
	ds_read_b128 v[216:219], v214 offset:55296
	ds_read_b128 v[220:223], v215 offset:53248
	ds_read_b128 v[224:227], v215 offset:55296
	buffer_load_dwordx4 v205, s[8:11], s82 offen lds
	s_mov_b32 m0, s42
	s_nop 0
	buffer_load_dwordx4 v207, s[8:11], s82 offen lds
	s_add_i32 s82, s82, s29
	s_mov_b32 m0, s45
	s_nop 0
	buffer_load_dwordx4 v205, s[8:11], s82 offen lds
	s_mov_b32 m0, s46
	s_nop 0
	buffer_load_dwordx4 v207, s[8:11], s82 offen lds
	s_mov_b32 m0, s43
	s_nop 0
	buffer_load_dwordx4 v204, s[48:51], s81 offen lds
	s_mov_b32 m0, s44
	s_nop 0
	buffer_load_dwordx4 v206, s[48:51], s81 offen lds
	s_waitcnt vmcnt(8)
	s_waitcnt lgkmcnt(0)
	s_barrier
	s_setprio 1
	s_waitcnt lgkmcnt(0)
	v_mfma_f32_16x16x32_bf16 v[76:79], v[116:119], v[180:183], v[76:79]
	v_mfma_f32_16x16x32_bf16 v[68:71], v[120:123], v[180:183], v[68:71]
	v_mfma_f32_16x16x32_bf16 v[60:63], v[116:119], v[184:187], v[60:63]
	v_mfma_f32_16x16x32_bf16 v[52:55], v[120:123], v[184:187], v[52:55]
	v_mfma_f32_16x16x32_bf16 v[44:47], v[116:119], v[196:199], v[44:47]
	v_mfma_f32_16x16x32_bf16 v[36:39], v[120:123], v[196:199], v[36:39]
	v_mfma_f32_16x16x32_bf16 v[24:27], v[116:119], v[216:219], v[24:27]
	v_mfma_f32_16x16x32_bf16 v[20:23], v[120:123], v[216:219], v[20:23]
	v_mfma_f32_16x16x32_bf16 v[76:79], v[140:143], v[188:191], v[76:79]
	v_mfma_f32_16x16x32_bf16 v[68:71], v[144:147], v[188:191], v[68:71]
	v_mfma_f32_16x16x32_bf16 v[60:63], v[140:143], v[192:195], v[60:63]
	v_mfma_f32_16x16x32_bf16 v[52:55], v[144:147], v[192:195], v[52:55]
	v_mfma_f32_16x16x32_bf16 v[44:47], v[140:143], v[220:223], v[44:47]
	v_mfma_f32_16x16x32_bf16 v[36:39], v[144:147], v[220:223], v[36:39]
	v_mfma_f32_16x16x32_bf16 v[24:27], v[140:143], v[224:227], v[24:27]
	v_mfma_f32_16x16x32_bf16 v[20:23], v[144:147], v[224:227], v[20:23]
	s_setprio 0
	s_setprio 1
	v_mfma_f32_16x16x32_bf16 v[80:83], v[164:167], v[180:183], v[80:83]
	v_mfma_f32_16x16x32_bf16 v[72:75], v[168:171], v[180:183], v[72:75]
	v_mfma_f32_16x16x32_bf16 v[64:67], v[164:167], v[184:187], v[64:67]
	v_mfma_f32_16x16x32_bf16 v[56:59], v[168:171], v[184:187], v[56:59]
	v_mfma_f32_16x16x32_bf16 v[48:51], v[164:167], v[196:199], v[48:51]
	v_mfma_f32_16x16x32_bf16 v[40:43], v[168:171], v[196:199], v[40:43]
	v_mfma_f32_16x16x32_bf16 v[28:31], v[164:167], v[216:219], v[28:31]
	v_mfma_f32_16x16x32_bf16 v[32:35], v[168:171], v[216:219], v[32:35]
	v_mfma_f32_16x16x32_bf16 v[80:83], v[172:175], v[188:191], v[80:83]
	v_mfma_f32_16x16x32_bf16 v[72:75], v[176:179], v[188:191], v[72:75]
	v_mfma_f32_16x16x32_bf16 v[64:67], v[172:175], v[192:195], v[64:67]
	v_mfma_f32_16x16x32_bf16 v[56:59], v[176:179], v[192:195], v[56:59]
	v_mfma_f32_16x16x32_bf16 v[48:51], v[172:175], v[220:223], v[48:51]
	v_mfma_f32_16x16x32_bf16 v[40:43], v[176:179], v[220:223], v[40:43]
	v_mfma_f32_16x16x32_bf16 v[28:31], v[172:175], v[224:227], v[28:31]
	v_mfma_f32_16x16x32_bf16 v[32:35], v[176:179], v[224:227], v[32:35]
	s_setprio 0
	s_barrier
